# m10 with the ds_read pipelining extended to ds_read2_b64 chains (145 sites)
# baseline (speedup 1.0000x reference)
; #define LAS __attribute__((address_space(3)))
; #define SCHED_FENCE() __builtin_amdgcn_sched_barrier(0)
; __device__ __forceinline__ f32x4 mfma16(bf16x8 a, bf16x8 b, f32x4 c) { return __builtin_amdgcn_mfma_f32_16x16x32_bf16(a, b, c, 0, 0, 0); }
; #define A2_LOADK(hp_, s_) do { const char* _g = (const char*)(kg0 + (size_t)(s_) * kstep + (hp_) * 256); _Pragma("unroll") for (int j = 0; j < 8; ++j) t8[j] = *(const u32x4*)(_g + (size_t)j * (16 * kld * 2) + kgo); } while (0)
; #define A2_LOADV(hp_, s_) do { const char* _g = (const char*)(vg0 + (size_t)(hp_) * 256 * vld + (size_t)(s_) * vstep); _Pragma("unroll") for (int j = 0; j < 8; ++j) t8[j] = *(const u32x4*)(_g + (size_t)j * (32 * vld * 2) + vgo); } while (0)
; #define A2_WRITEK(buf_) do { _Pragma("unroll") for (int j = 0; j < 8; ++j) *(LAS u32x4*)((buf_) + klo + j * (16 * 272)) = t8[j]; } while (0)
; template <bool NA> ...
;     ...
;         for (int ks = 0; ks < NSTEP; ++ks) {
;             LAS unsigned char* cur = lds + cb * ABUF2; LAS unsigned char* nxt = lds + (cb ^ 1) * ABUF2;
;             if (ks < NSTEP - 1) A2_LOADK(hp, ks + 1); else A2_LOADV(hp, 0);
;             SCHED_FENCE();
; #pragma unroll
;             for (int g = 0; g < NGRP; ++g) {
;                 const int gi = ks * NGRP + g, koff = NA ? g * 64 + w0 : g * 32;
;                 const LAS unsigned char* kp = cur + (hh * 128 + koff + fr) * 272 + fq * 16;
;                 bf16x8 kf[2][4];
; #pragma unroll
;                 for (int a = 0; a < 2; ++a)
; #pragma unroll
;                     for (int dc = 0; dc < 4; ++dc) kf[a][dc] = *(const LAS bf16x8*)(kp + a * 16 * 272 + dc * 64);
;                 f32x4 s0 = (f32x4){0.f, 0.f, 0.f, 0.f}, s1 = (f32x4){0.f, 0.f, 0.f, 0.f};
; #pragma unroll
;                 for (int dc = 0; dc < 4; ++dc) { s0 = mfma16(kf[0][dc], qf[dc], s0); s1 = mfma16(kf[1][dc], qf[dc], s1); }
;                 if (NA) { const LAS float* br = rpb + ((hp * 2 + hh) * 15 + brow0 + 2 * ks + g) * 32;
; #pragma unroll
;                     for (int e = 0; e < 4; ++e) { s0[e] += br[bidx[e]]; s1[e] += br[bidx[4 + e]]; } }
;                 sc[gi][0] = s0; sc[gi][1] = s1;
;             }
;             SCHED_FENCE();
;             if (ks < NSTEP - 1) A2_WRITEK(nxt); else A2_WRITEV(nxt);
;             __syncthreads(); cb ^= 1;
.LBB0_221:
	v_lshl_add_u64 v[112:113], s[66:67], 0, v[108:109]
	v_add_co_u32_e32 v16, vcc, 0xe8e0000, v112
	s_nop 1
	v_addc_co_u32_e32 v17, vcc, 0, v113, vcc
	v_add_co_u32_e32 v18, vcc, 0xe8f8000, v112
	s_nop 1
	v_addc_co_u32_e32 v19, vcc, 0, v113, vcc
	global_load_dwordx4 v[44:47], v[16:17], off offset:2048
	global_load_dwordx4 v[48:51], v[18:19], off offset:2048
	v_add_co_u32_e32 v16, vcc, 0xe910000, v112
	s_nop 1
	v_addc_co_u32_e32 v17, vcc, 0, v113, vcc
	v_add_co_u32_e32 v18, vcc, 0xe928000, v112
	s_nop 1
	v_addc_co_u32_e32 v19, vcc, 0, v113, vcc
	global_load_dwordx4 v[52:55], v[16:17], off offset:2048
	global_load_dwordx4 v[56:59], v[18:19], off offset:2048
	v_add_co_u32_e32 v16, vcc, 0xe940000, v112
	s_nop 1
	v_addc_co_u32_e32 v17, vcc, 0, v113, vcc
	v_add_co_u32_e32 v18, vcc, 0xe958000, v112
	s_nop 1
	v_addc_co_u32_e32 v19, vcc, 0, v113, vcc
	global_load_dwordx4 v[60:63], v[16:17], off offset:2048
	global_load_dwordx4 v[64:67], v[18:19], off offset:2048
	v_add_co_u32_e32 v16, vcc, 0xe970000, v112
	s_nop 1
	v_addc_co_u32_e32 v17, vcc, 0, v113, vcc
	v_add_co_u32_e32 v18, vcc, 0xe988000, v112
	s_nop 1
	v_addc_co_u32_e32 v19, vcc, 0, v113, vcc
	global_load_dwordx4 v[68:71], v[16:17], off offset:2048
	global_load_dwordx4 v[72:75], v[18:19], off offset:2048
	v_lshl_add_u64 v[16:17], s[66:67], 0, v[104:105]
	s_waitcnt vmcnt(21)
	v_add_u32_e32 v42, v155, v117
	ds_read_b128 v[18:21], v42
	ds_read_b128 v[22:25], v42 offset:64
	ds_read_b128 v[26:29], v42 offset:4352
	ds_read_b128 v[30:33], v42 offset:4416
	v_add_u32_e32 v35, s13, v144
	v_add_u32_e32 v41, s13, v164
	s_waitcnt vmcnt(19) lgkmcnt(3)
	v_mfma_f32_16x16x32_bf16 v[18:21], v[18:21], v[0:3], 0
	v_add_u32_e32 v40, s13, v153
	v_add_u32_e32 v161, 0x23380, v41
	v_add_u32_e32 v162, 0x23380, v40
	s_waitcnt lgkmcnt(1)
	v_mfma_f32_16x16x32_bf16 v[26:29], v[26:29], v[0:3], 0
	s_waitcnt vmcnt(18)
	v_mfma_f32_16x16x32_bf16 v[18:21], v[22:25], v[4:7], v[18:21]
	ds_read_b128 v[22:25], v42 offset:128
	ds_read_b128 v[36:39], v42 offset:4480
	ds_read_b128 v[76:79], v42 offset:192
	ds_read_b128 v[80:83], v42 offset:4544
	ds_read_b128 v[84:87], v42 offset:21824
	s_waitcnt lgkmcnt(5)
	v_mfma_f32_16x16x32_bf16 v[30:33], v[30:33], v[4:7], v[26:29]
	s_waitcnt vmcnt(17) lgkmcnt(4)
	v_mfma_f32_16x16x32_bf16 v[18:21], v[22:25], v[8:11], v[18:21]
	s_nop 0
	v_add_u32_e32 v29, s13, v152
	v_add_u32_e32 v26, 0x23380, v29
	v_add_u32_e32 v27, 0x23380, v35
	s_waitcnt lgkmcnt(3)
	v_mfma_f32_16x16x32_bf16 v[22:25], v[36:39], v[8:11], v[30:33]
	v_add_u32_e32 v36, s13, v163
	v_add_u32_e32 v37, s13, v165
	v_add_u32_e32 v38, s13, v167
	ds_read_b128 v[30:33], v42 offset:17408
	s_waitcnt vmcnt(16) lgkmcnt(3)
	v_mfma_f32_16x16x32_bf16 v[76:79], v[76:79], v[12:15], v[18:21]
	v_add_u32_e32 v39, s13, v166
	v_add_u32_e32 v28, 0x23380, v36
	v_add_u32_e32 v34, 0x23380, v37
	ds_read_b128 v[18:21], v42 offset:21760
	s_waitcnt lgkmcnt(3)
	v_mfma_f32_16x16x32_bf16 v[80:83], v[80:83], v[12:15], v[22:25]
	v_add_u32_e32 v43, 0x23380, v38
	v_add_u32_e32 v160, 0x23380, v39
	s_nop 0
	ds_read_b128 v[22:25], v42 offset:17472
	s_waitcnt lgkmcnt(2)
	v_mfma_f32_16x16x32_bf16 v[30:33], v[30:33], v[0:3], 0
	s_waitcnt lgkmcnt(1)
	v_mfma_f32_16x16x32_bf16 v[18:21], v[18:21], v[0:3], 0
	s_waitcnt lgkmcnt(0)
	v_mfma_f32_16x16x32_bf16 v[22:25], v[22:25], v[4:7], v[30:33]
	s_nop 3
	ds_read_b128 v[30:33], v42 offset:17536
	ds_read_b128 v[88:91], v42 offset:21888
	v_mfma_f32_16x16x32_bf16 v[18:21], v[84:87], v[4:7], v[18:21]
	ds_read_b32 v26, v26
	ds_read_b32 v27, v27
	ds_read_b32 v28, v28
	ds_read_b32 v34, v34
	ds_read_b32 v43, v43
	ds_read_b32 v160, v160
	ds_read_b32 v161, v161
	ds_read_b32 v162, v162
	ds_read_b128 v[84:87], v42 offset:17600
	ds_read_b128 v[168:171], v42 offset:21952
	s_waitcnt lgkmcnt(11)
	v_mfma_f32_16x16x32_bf16 v[30:33], v[30:33], v[8:11], v[22:25]
	s_waitcnt lgkmcnt(10)
	v_mfma_f32_16x16x32_bf16 v[88:91], v[88:91], v[8:11], v[18:21]
	s_waitcnt lgkmcnt(9)
	v_add_f32_e32 v24, v76, v26
	s_waitcnt lgkmcnt(8)
	v_add_f32_e32 v22, v80, v27
	s_waitcnt lgkmcnt(7)
	v_add_f32_e32 v25, v77, v28
	s_waitcnt lgkmcnt(1)
	v_mfma_f32_16x16x32_bf16 v[84:87], v[84:87], v[12:15], v[30:33]
	v_add_u32_e32 v26, 0x23400, v29
	v_add_u32_e32 v27, 0x23400, v35
	v_add_u32_e32 v28, 0x23400, v36
	v_add_u32_e32 v30, 0x23400, v37
	v_add_f32_e32 v23, v81, v34
	v_add_f32_e32 v20, v78, v43
	v_add_f32_e32 v21, v82, v160
	v_add_u32_e32 v31, 0x23400, v38
	v_add_u32_e32 v32, 0x23400, v39
	v_add_u32_e32 v33, 0x23400, v41
	v_add_u32_e32 v34, 0x23400, v40
	ds_read_b32 v26, v26
	ds_read_b32 v27, v27
	ds_read_b32 v28, v28
	ds_read_b32 v30, v30
	ds_read_b32 v43, v31
	ds_read_b32 v80, v32
	ds_read_b32 v81, v33
	ds_read_b32 v82, v34
	v_add_f32_e32 v19, v79, v161
	s_waitcnt lgkmcnt(8)
	v_mfma_f32_16x16x32_bf16 v[76:79], v[168:171], v[12:15], v[88:91]
	v_add_f32_e32 v18, v83, v162
	s_waitcnt lgkmcnt(7)
	v_add_f32_e32 v34, v84, v26
	s_waitcnt lgkmcnt(5)
	v_add_f32_e32 v32, v85, v28
	s_nop 2
	v_add_f32_e32 v33, v76, v27
	s_waitcnt lgkmcnt(4)
	v_add_f32_e32 v31, v77, v30
	s_waitcnt lgkmcnt(3)
	v_add_f32_e32 v30, v86, v43
	s_waitcnt lgkmcnt(2)
	v_add_f32_e32 v28, v78, v80
	s_waitcnt lgkmcnt(1)
	v_add_f32_e32 v27, v87, v81
	s_waitcnt lgkmcnt(0)
	v_add_f32_e32 v26, v79, v82
	s_add_i32 s7, 0, 0x11000
	v_add_u32_e32 v160, s7, v100
	s_mov_b32 s8, 0xe9a0000
	s_waitcnt vmcnt(7)
	ds_write_b128 v160, v[44:47]
	s_waitcnt vmcnt(6)
	ds_write_b128 v160, v[48:51] offset:4352
	s_waitcnt vmcnt(5)
	ds_write_b128 v160, v[52:55] offset:8704
	s_waitcnt vmcnt(4)
	ds_write_b128 v160, v[56:59] offset:13056
	s_waitcnt vmcnt(3)
	ds_write_b128 v160, v[60:63] offset:17408
	s_waitcnt vmcnt(2)
	ds_write_b128 v160, v[64:67] offset:21760
	s_waitcnt vmcnt(1)
	ds_write_b128 v160, v[68:71] offset:26112
	s_waitcnt vmcnt(0)
	ds_write_b128 v160, v[72:75] offset:30464
	v_add_co_u32_e32 v44, vcc, s8, v112
	s_mov_b32 s8, 0xe9b8000
	s_nop 0
	v_addc_co_u32_e32 v45, vcc, 0, v113, vcc
	v_add_co_u32_e32 v48, vcc, s8, v112
	s_mov_b32 s8, 0xe9d0000
	s_nop 0
	v_addc_co_u32_e32 v49, vcc, 0, v113, vcc
	v_add_co_u32_e32 v52, vcc, s8, v112
	s_mov_b32 s8, 0xe9e8000
	s_nop 0
	v_addc_co_u32_e32 v53, vcc, 0, v113, vcc
	v_add_co_u32_e32 v54, vcc, s8, v112
	s_mov_b32 s8, 0xea00000
	s_nop 0
	v_addc_co_u32_e32 v55, vcc, 0, v113, vcc
	s_waitcnt lgkmcnt(0)
	s_barrier
; #define LAS __attribute__((address_space(3)))
; #define SCHED_FENCE() __builtin_amdgcn_sched_barrier(0)
; __device__ __forceinline__ f32x4 mfma16(bf16x8 a, bf16x8 b, f32x4 c) { return __builtin_amdgcn_mfma_f32_16x16x32_bf16(a, b, c, 0, 0, 0); }
; #define A2_LOADK(hp_, s_) do { const char* _g = (const char*)(kg0 + (size_t)(s_) * kstep + (hp_) * 256); _Pragma("unroll") for (int j = 0; j < 8; ++j) t8[j] = *(const u32x4*)(_g + (size_t)j * (16 * kld * 2) + kgo); } while (0)
; #define A2_LOADV(hp_, s_) do { const char* _g = (const char*)(vg0 + (size_t)(hp_) * 256 * vld + (size_t)(s_) * vstep); _Pragma("unroll") for (int j = 0; j < 8; ++j) t8[j] = *(const u32x4*)(_g + (size_t)j * (32 * vld * 2) + vgo); } while (0)
; #define A2_WRITEK(buf_) do { _Pragma("unroll") for (int j = 0; j < 8; ++j) *(LAS u32x4*)((buf_) + klo + j * (16 * 272)) = t8[j]; } while (0)
; template <bool NA> ...
;     ...
;         for (int ks = 0; ks < NSTEP; ++ks) {
;             LAS unsigned char* cur = lds + cb * ABUF2; LAS unsigned char* nxt = lds + (cb ^ 1) * ABUF2;
;             if (ks < NSTEP - 1) A2_LOADK(hp, ks + 1); else A2_LOADV(hp, 0);
;             SCHED_FENCE();
; #pragma unroll
;             for (int g = 0; g < NGRP; ++g) {
;                 const int gi = ks * NGRP + g, koff = NA ? g * 64 + w0 : g * 32;
;                 const LAS unsigned char* kp = cur + (hh * 128 + koff + fr) * 272 + fq * 16;
;                 bf16x8 kf[2][4];
; #pragma unroll
;                 for (int a = 0; a < 2; ++a)
; #pragma unroll
;                     for (int dc = 0; dc < 4; ++dc) kf[a][dc] = *(const LAS bf16x8*)(kp + a * 16 * 272 + dc * 64);
;                 f32x4 s0 = (f32x4){0.f, 0.f, 0.f, 0.f}, s1 = (f32x4){0.f, 0.f, 0.f, 0.f};
; #pragma unroll
;                 for (int dc = 0; dc < 4; ++dc) { s0 = mfma16(kf[0][dc], qf[dc], s0); s1 = mfma16(kf[1][dc], qf[dc], s1); }
;                 if (NA) { const LAS float* br = rpb + ((hp * 2 + hh) * 15 + brow0 + 2 * ks + g) * 32;
; #pragma unroll
;                     for (int e = 0; e < 4; ++e) { s0[e] += br[bidx[e]]; s1[e] += br[bidx[4 + e]]; } }
;                 sc[gi][0] = s0; sc[gi][1] = s1;
;             }
;             SCHED_FENCE();
;             if (ks < NSTEP - 1) A2_WRITEK(nxt); else A2_WRITEV(nxt);
;             __syncthreads(); cb ^= 1;
	global_load_dwordx4 v[44:47], v[44:45], off offset:2048
	s_nop 0
	global_load_dwordx4 v[48:51], v[48:49], off offset:2048
	s_nop 0
	global_load_dwordx4 v[56:59], v[52:53], off offset:2048
	global_load_dwordx4 v[60:63], v[54:55], off offset:2048
	v_add_co_u32_e32 v52, vcc, s8, v112
	s_mov_b32 s8, 0xea18000
	s_nop 0
	v_addc_co_u32_e32 v53, vcc, 0, v113, vcc
	v_add_co_u32_e32 v54, vcc, s8, v112
	s_mov_b32 s8, 0xea30000
	s_nop 0
	v_addc_co_u32_e32 v55, vcc, 0, v113, vcc
	global_load_dwordx4 v[76:79], v[52:53], off offset:2048
	global_load_dwordx4 v[80:83], v[54:55], off offset:2048
	v_add_co_u32_e32 v52, vcc, s8, v112
	s_mov_b32 s8, 0xea48000
	s_nop 0
	v_addc_co_u32_e32 v53, vcc, 0, v113, vcc
	v_add_co_u32_e32 v54, vcc, s8, v112
	s_nop 1
	v_addc_co_u32_e32 v55, vcc, 0, v113, vcc
	global_load_dwordx4 v[84:87], v[52:53], off offset:2048
	global_load_dwordx4 v[88:91], v[54:55], off offset:2048
	v_add_u32_e32 v43, v159, v117
	ds_read_b128 v[52:55], v43
	ds_read_b128 v[64:67], v43 offset:64
	ds_read_b128 v[68:71], v43 offset:4352
	ds_read_b128 v[72:75], v43 offset:4416
	v_add_u32_e32 v161, 0x23480, v29
	v_add_u32_e32 v162, 0x23480, v35
	s_waitcnt lgkmcnt(3)
	v_mfma_f32_16x16x32_bf16 v[52:55], v[52:55], v[0:3], 0
	v_add_u32_e32 v176, 0x23480, v36
	v_add_u32_e32 v177, 0x23480, v37
	v_add_u32_e32 v178, 0x23480, v38
	s_waitcnt lgkmcnt(2)
	v_mfma_f32_16x16x32_bf16 v[52:55], v[64:67], v[4:7], v[52:55]
	ds_read_b128 v[64:67], v43 offset:128
	v_add_u32_e32 v179, 0x23480, v39
	v_add_u32_e32 v180, 0x23480, v41
	s_waitcnt lgkmcnt(2)
	v_mfma_f32_16x16x32_bf16 v[68:71], v[68:71], v[0:3], 0
	s_waitcnt lgkmcnt(1)
	v_mfma_f32_16x16x32_bf16 v[68:71], v[72:75], v[4:7], v[68:71]
	ds_read_b128 v[72:75], v43 offset:4480
	ds_read_b128 v[168:171], v43 offset:192
	s_waitcnt lgkmcnt(2)
	v_mfma_f32_16x16x32_bf16 v[52:55], v[64:67], v[8:11], v[52:55]
	ds_read_b128 v[64:67], v43 offset:4544
	s_waitcnt lgkmcnt(2)
	v_mfma_f32_16x16x32_bf16 v[68:71], v[72:75], v[8:11], v[68:71]
	ds_read_b128 v[72:75], v43 offset:17408
	s_waitcnt lgkmcnt(2)
	v_mfma_f32_16x16x32_bf16 v[52:55], v[168:171], v[12:15], v[52:55]
	ds_read_b128 v[168:171], v43 offset:17472
	ds_read_b128 v[172:175], v43 offset:21760
	s_waitcnt lgkmcnt(3)
	v_mfma_f32_16x16x32_bf16 v[66:69], v[64:67], v[12:15], v[68:71]
	v_add_u32_e32 v64, 0x23480, v40
	s_waitcnt lgkmcnt(2)
	v_mfma_f32_16x16x32_bf16 v[70:73], v[72:75], v[0:3], 0
	ds_read_b32 v65, v161
	ds_read_b32 v74, v162
	ds_read_b32 v75, v176
	ds_read_b32 v161, v177
	ds_read_b32 v162, v178
	ds_read_b32 v184, v179
	ds_read_b32 v185, v180
	ds_read_b32 v186, v64
	ds_read_b128 v[176:179], v43 offset:21824
	ds_read_b128 v[180:183], v43 offset:17536
	s_waitcnt lgkmcnt(9)
	v_add_f32_e32 v64, v52, v65
	v_mfma_f32_16x16x32_bf16 v[172:175], v[172:175], v[0:3], 0
	s_waitcnt lgkmcnt(8)
	v_add_f32_e32 v52, v66, v74
	s_waitcnt lgkmcnt(7)
	v_add_f32_e32 v65, v53, v75
	s_waitcnt lgkmcnt(6)
	v_add_f32_e32 v53, v67, v161
	v_mfma_f32_16x16x32_bf16 v[70:73], v[168:171], v[4:7], v[70:73]
	ds_read_b128 v[168:171], v43 offset:21888
	s_waitcnt lgkmcnt(6)
	v_add_f32_e32 v66, v54, v162
	s_waitcnt lgkmcnt(5)
	v_add_f32_e32 v54, v68, v184
	s_waitcnt lgkmcnt(2)
	v_mfma_f32_16x16x32_bf16 v[172:175], v[176:179], v[4:7], v[172:175]
	ds_read_b128 v[176:179], v43 offset:17600
	v_add_f32_e32 v67, v55, v185
	v_add_f32_e32 v55, v69, v186
	s_waitcnt lgkmcnt(2)
	v_mfma_f32_16x16x32_bf16 v[70:73], v[180:183], v[8:11], v[70:73]
	ds_read_b128 v[180:183], v43 offset:21952
	v_add_u32_e32 v68, 0x23500, v29
	v_add_u32_e32 v69, 0x23500, v35
	s_waitcnt lgkmcnt(2)
	v_mfma_f32_16x16x32_bf16 v[168:171], v[168:171], v[8:11], v[172:175]
	v_add_u32_e32 v74, 0x23500, v36
	v_add_u32_e32 v75, 0x23500, v40
	s_waitcnt lgkmcnt(1)
	v_mfma_f32_16x16x32_bf16 v[172:175], v[176:179], v[12:15], v[70:73]
	s_nop 2
	v_add_u32_e32 v70, 0x23500, v37
	v_add_u32_e32 v71, 0x23500, v38
	v_add_u32_e32 v72, 0x23500, v39
	v_add_u32_e32 v73, 0x23500, v41
	ds_read_b32 v68, v68
	ds_read_b32 v69, v69
	ds_read_b32 v161, v74
	ds_read_b32 v70, v70
	ds_read_b32 v71, v71
	ds_read_b32 v162, v72
	ds_read_b32 v176, v73
	ds_read_b32 v177, v75
	s_waitcnt lgkmcnt(8)
	v_mfma_f32_16x16x32_bf16 v[168:171], v[180:183], v[12:15], v[168:171]
	s_waitcnt lgkmcnt(7)
	v_add_f32_e32 v75, v172, v68
	s_waitcnt lgkmcnt(5)
	v_add_f32_e32 v73, v173, v161
	s_waitcnt lgkmcnt(3)
	v_add_f32_e32 v71, v174, v71
	s_nop 1
	v_add_f32_e32 v74, v168, v69
	v_add_f32_e32 v72, v169, v70
	s_waitcnt lgkmcnt(2)
	v_add_f32_e32 v70, v170, v162
	s_waitcnt lgkmcnt(1)
	v_add_f32_e32 v69, v175, v176
	s_waitcnt lgkmcnt(0)
	v_add_f32_e32 v68, v171, v177
	s_mov_b32 s8, 0xea60000
	s_waitcnt vmcnt(7)
	ds_write_b128 v154, v[44:47]
	s_waitcnt vmcnt(6)
	ds_write_b128 v154, v[48:51] offset:4352
	s_waitcnt vmcnt(5)
	ds_write_b128 v154, v[56:59] offset:8704
	s_waitcnt vmcnt(4)
	ds_write_b128 v154, v[60:63] offset:13056
	s_waitcnt vmcnt(3)
	ds_write_b128 v154, v[76:79] offset:17408
	s_waitcnt vmcnt(2)
	ds_write_b128 v154, v[80:83] offset:21760
	s_waitcnt vmcnt(1)
	ds_write_b128 v154, v[84:87] offset:26112
	s_waitcnt vmcnt(0)
	ds_write_b128 v154, v[88:91] offset:30464
	v_add_co_u32_e32 v44, vcc, s8, v112
	s_mov_b32 s8, 0xea78000
	s_nop 0
	v_addc_co_u32_e32 v45, vcc, 0, v113, vcc
	v_add_co_u32_e32 v48, vcc, s8, v112
	s_mov_b32 s8, 0xea90000
	s_nop 0
	v_addc_co_u32_e32 v49, vcc, 0, v113, vcc
	v_add_co_u32_e32 v56, vcc, s8, v112
	s_mov_b32 s8, 0xeaa8000
	s_nop 0
	v_addc_co_u32_e32 v57, vcc, 0, v113, vcc
	v_add_co_u32_e32 v60, vcc, s8, v112
	s_mov_b32 s8, 0xeac0000
	s_nop 0
	v_addc_co_u32_e32 v61, vcc, 0, v113, vcc
	v_add_co_u32_e32 v76, vcc, s8, v112
	s_mov_b32 s8, 0xead8000
	s_nop 0
	v_addc_co_u32_e32 v77, vcc, 0, v113, vcc
	v_add_co_u32_e32 v82, vcc, s8, v112
	s_mov_b32 s8, 0xeaf0000
	s_nop 0
	v_addc_co_u32_e32 v83, vcc, 0, v113, vcc
	s_waitcnt lgkmcnt(0)
	s_barrier
; #define LAS __attribute__((address_space(3)))
; #define SCHED_FENCE() __builtin_amdgcn_sched_barrier(0)
; __device__ __forceinline__ f32x4 mfma16(bf16x8 a, bf16x8 b, f32x4 c) { return __builtin_amdgcn_mfma_f32_16x16x32_bf16(a, b, c, 0, 0, 0); }
; #define A2_LOADK(hp_, s_) do { const char* _g = (const char*)(kg0 + (size_t)(s_) * kstep + (hp_) * 256); _Pragma("unroll") for (int j = 0; j < 8; ++j) t8[j] = *(const u32x4*)(_g + (size_t)j * (16 * kld * 2) + kgo); } while (0)
; #define A2_LOADV(hp_, s_) do { const char* _g = (const char*)(vg0 + (size_t)(hp_) * 256 * vld + (size_t)(s_) * vstep); _Pragma("unroll") for (int j = 0; j < 8; ++j) t8[j] = *(const u32x4*)(_g + (size_t)j * (32 * vld * 2) + vgo); } while (0)
; #define A2_WRITEK(buf_) do { _Pragma("unroll") for (int j = 0; j < 8; ++j) *(LAS u32x4*)((buf_) + klo + j * (16 * 272)) = t8[j]; } while (0)
; template <bool NA> ...
;     ...
;         for (int ks = 0; ks < NSTEP; ++ks) {
;             LAS unsigned char* cur = lds + cb * ABUF2; LAS unsigned char* nxt = lds + (cb ^ 1) * ABUF2;
;             if (ks < NSTEP - 1) A2_LOADK(hp, ks + 1); else A2_LOADV(hp, 0);
;             SCHED_FENCE();
; #pragma unroll
;             for (int g = 0; g < NGRP; ++g) {
;                 const int gi = ks * NGRP + g, koff = NA ? g * 64 + w0 : g * 32;
;                 const LAS unsigned char* kp = cur + (hh * 128 + koff + fr) * 272 + fq * 16;
;                 bf16x8 kf[2][4];
; #pragma unroll
;                 for (int a = 0; a < 2; ++a)
; #pragma unroll
;                     for (int dc = 0; dc < 4; ++dc) kf[a][dc] = *(const LAS bf16x8*)(kp + a * 16 * 272 + dc * 64);
;                 f32x4 s0 = (f32x4){0.f, 0.f, 0.f, 0.f}, s1 = (f32x4){0.f, 0.f, 0.f, 0.f};
; #pragma unroll
;                 for (int dc = 0; dc < 4; ++dc) { s0 = mfma16(kf[0][dc], qf[dc], s0); s1 = mfma16(kf[1][dc], qf[dc], s1); }
;                 if (NA) { const LAS float* br = rpb + ((hp * 2 + hh) * 15 + brow0 + 2 * ks + g) * 32;
; #pragma unroll
;                     for (int e = 0; e < 4; ++e) { s0[e] += br[bidx[e]]; s1[e] += br[bidx[4 + e]]; } }
;                 sc[gi][0] = s0; sc[gi][1] = s1;
;             }
;             SCHED_FENCE();
;             if (ks < NSTEP - 1) A2_WRITEK(nxt); else A2_WRITEV(nxt);
;             __syncthreads(); cb ^= 1;
	global_load_dwordx4 v[44:47], v[44:45], off offset:2048
	s_nop 0
	global_load_dwordx4 v[48:51], v[48:49], off offset:2048
	s_nop 0
	global_load_dwordx4 v[56:59], v[56:57], off offset:2048
	s_nop 0
	global_load_dwordx4 v[60:63], v[60:61], off offset:2048
	s_nop 0
	global_load_dwordx4 v[78:81], v[76:77], off offset:2048
	s_nop 0
	global_load_dwordx4 v[82:85], v[82:83], off offset:2048
	v_add_co_u32_e32 v76, vcc, s8, v112
	s_mov_b32 s8, 0xeb08000
	s_nop 0
	v_addc_co_u32_e32 v77, vcc, 0, v113, vcc
	v_add_co_u32_e32 v90, vcc, s8, v112
	s_nop 1
	v_addc_co_u32_e32 v91, vcc, 0, v113, vcc
	global_load_dwordx4 v[86:89], v[76:77], off offset:2048
	global_load_dwordx4 v[168:171], v[90:91], off offset:2048
	ds_read_b128 v[172:175], v42
	ds_read_b128 v[176:179], v42 offset:64
	ds_read_b128 v[180:183], v42 offset:4352
	ds_read_b128 v[184:187], v42 offset:4416
	v_add_u32_e32 v76, 0x23580, v29
	v_add_u32_e32 v77, 0x23580, v35
	s_waitcnt lgkmcnt(3)
	v_mfma_f32_16x16x32_bf16 v[172:175], v[172:175], v[0:3], 0
	v_add_u32_e32 v90, 0x23580, v36
	v_add_u32_e32 v91, 0x23580, v37
	v_add_u32_e32 v161, 0x23580, v38
	s_waitcnt lgkmcnt(2)
	v_mfma_f32_16x16x32_bf16 v[172:175], v[176:179], v[4:7], v[172:175]
	ds_read_b128 v[176:179], v42 offset:128
	v_add_u32_e32 v162, 0x23580, v39
	v_add_u32_e32 v192, 0x23580, v41
	s_waitcnt lgkmcnt(2)
	v_mfma_f32_16x16x32_bf16 v[180:183], v[180:183], v[0:3], 0
	v_add_u32_e32 v193, 0x23580, v40
	s_waitcnt lgkmcnt(1)
	v_mfma_f32_16x16x32_bf16 v[180:183], v[184:187], v[4:7], v[180:183]
	ds_read_b128 v[184:187], v42 offset:4480
	ds_read_b128 v[188:191], v42 offset:192
	s_waitcnt lgkmcnt(2)
	v_mfma_f32_16x16x32_bf16 v[172:175], v[176:179], v[8:11], v[172:175]
	ds_read_b128 v[176:179], v42 offset:4544
	s_waitcnt lgkmcnt(2)
	v_mfma_f32_16x16x32_bf16 v[180:183], v[184:187], v[8:11], v[180:183]
	ds_read_b128 v[184:187], v42 offset:17408
	s_waitcnt lgkmcnt(2)
	v_mfma_f32_16x16x32_bf16 v[172:175], v[188:191], v[12:15], v[172:175]
	s_waitcnt lgkmcnt(1)
	v_mfma_f32_16x16x32_bf16 v[176:179], v[176:179], v[12:15], v[180:183]
	s_nop 2
	ds_read_b128 v[180:183], v42 offset:17472
	ds_read_b128 v[188:191], v42 offset:21760
	ds_read_b32 v76, v76
	ds_read_b32 v77, v77
	ds_read_b32 v90, v90
	ds_read_b32 v91, v91
	ds_read_b32 v161, v161
	ds_read_b32 v162, v162
	ds_read_b32 v200, v192
	ds_read_b32 v201, v193
	ds_read_b128 v[192:195], v42 offset:21824
	s_waitcnt lgkmcnt(11)
	v_mfma_f32_16x16x32_bf16 v[184:187], v[184:187], v[0:3], 0
	ds_read_b128 v[196:199], v42 offset:17536
	s_waitcnt lgkmcnt(9)
	v_add_f32_e32 v222, v172, v76
	s_waitcnt lgkmcnt(7)
	v_add_f32_e32 v90, v173, v90
	v_mfma_f32_16x16x32_bf16 v[180:183], v[180:183], v[4:7], v[184:187]
	s_waitcnt lgkmcnt(5)
	v_add_f32_e32 v224, v174, v161
	s_waitcnt lgkmcnt(3)
	v_add_f32_e32 v225, v175, v200
	ds_read_b128 v[172:175], v42 offset:17600
	ds_read_b128 v[184:187], v42 offset:21888
	v_mfma_f32_16x16x32_bf16 v[188:191], v[188:191], v[0:3], 0
	v_add_f32_e32 v223, v176, v77
	v_add_f32_e32 v91, v177, v91
	v_add_f32_e32 v162, v178, v162
	s_waitcnt lgkmcnt(4)
	v_add_f32_e32 v226, v179, v201
	ds_read_b128 v[176:179], v42 offset:21952
	s_waitcnt lgkmcnt(4)
	v_mfma_f32_16x16x32_bf16 v[188:191], v[192:195], v[4:7], v[188:191]
	v_add_u32_e32 v42, 0x23600, v29
	v_add_u32_e32 v76, 0x23600, v35
	v_add_u32_e32 v77, 0x23600, v36
	s_waitcnt lgkmcnt(3)
	v_mfma_f32_16x16x32_bf16 v[180:183], v[196:199], v[8:11], v[180:183]
	v_add_u32_e32 v161, 0x23600, v37
	s_waitcnt lgkmcnt(1)
	v_mfma_f32_16x16x32_bf16 v[184:187], v[184:187], v[8:11], v[188:191]
	v_mfma_f32_16x16x32_bf16 v[172:175], v[172:175], v[12:15], v[180:183]
	s_nop 3
	v_add_u32_e32 v180, 0x23600, v38
	v_add_u32_e32 v181, 0x23600, v39
	v_add_u32_e32 v182, 0x23600, v41
	v_add_u32_e32 v183, 0x23600, v40
	ds_read_b32 v42, v42
	ds_read_b32 v76, v76
	ds_read_b32 v77, v77
	ds_read_b32 v161, v161
	ds_read_b32 v180, v180
	ds_read_b32 v181, v181
	ds_read_b32 v182, v182
	ds_read_b32 v183, v183
	s_waitcnt lgkmcnt(8)
	v_mfma_f32_16x16x32_bf16 v[176:179], v[176:179], v[12:15], v[184:187]
	s_waitcnt lgkmcnt(5)
	v_add_f32_e32 v229, v173, v77
	v_add_f32_e32 v227, v172, v42
	s_waitcnt lgkmcnt(1)
	v_add_f32_e32 v77, v175, v182
	v_add_f32_e32 v231, v174, v180
	s_nop 1
	v_add_f32_e32 v228, v176, v76
	s_waitcnt lgkmcnt(0)
	v_add_f32_e32 v76, v179, v183
	v_add_f32_e32 v230, v177, v161
	v_add_f32_e32 v232, v178, v181
	s_mov_b32 s8, 0x14820000
	s_waitcnt vmcnt(7)
	ds_write_b128 v160, v[44:47]
	s_waitcnt vmcnt(6)
	ds_write_b128 v160, v[48:51] offset:4352
	s_waitcnt vmcnt(5)
	ds_write_b128 v160, v[56:59] offset:8704
	s_waitcnt vmcnt(4)
	ds_write_b128 v160, v[60:63] offset:13056
	s_waitcnt vmcnt(3)
	ds_write_b128 v160, v[78:81] offset:17408
	s_waitcnt vmcnt(2)
	ds_write_b128 v160, v[82:85] offset:21760
	s_waitcnt vmcnt(1)
	ds_write_b128 v160, v[86:89] offset:26112
	s_waitcnt vmcnt(0)
	ds_write_b128 v160, v[168:171] offset:30464
	v_add_co_u32_e32 v44, vcc, s8, v16
	s_mov_b32 s8, 0x14920000
	s_nop 0
	v_addc_co_u32_e32 v45, vcc, 0, v17, vcc
	v_add_co_u32_e32 v46, vcc, s8, v16
	s_mov_b32 s8, 0x14a20000
	s_nop 0
	v_addc_co_u32_e32 v47, vcc, 0, v17, vcc
	v_add_co_u32_e32 v48, vcc, s8, v16
	s_mov_b32 s8, 0x14b20000
	s_nop 0
	v_addc_co_u32_e32 v49, vcc, 0, v17, vcc
	v_add_co_u32_e32 v50, vcc, s8, v16
	s_mov_b32 s8, 0x14c20000
	s_nop 0
	v_addc_co_u32_e32 v51, vcc, 0, v17, vcc
	v_add_co_u32_e32 v56, vcc, s8, v16
	s_mov_b32 s8, 0x14d20000
	s_nop 0
	v_addc_co_u32_e32 v57, vcc, 0, v17, vcc
	v_add_co_u32_e32 v58, vcc, s8, v16
	s_mov_b32 s8, 0x14e20000
	s_nop 0
	v_addc_co_u32_e32 v59, vcc, 0, v17, vcc
	v_add_co_u32_e32 v60, vcc, s8, v16
	s_mov_b32 s8, 0x14f20000
	s_nop 0
	v_addc_co_u32_e32 v61, vcc, 0, v17, vcc
	v_add_co_u32_e32 v62, vcc, s8, v16
	s_waitcnt lgkmcnt(0)
	s_barrier
; #define LAS __attribute__((address_space(3)))
; #define SCHED_FENCE() __builtin_amdgcn_sched_barrier(0)
; __device__ __forceinline__ float shfl_xor_l(float v, int lane, int mask) { return __int_as_float(__builtin_amdgcn_ds_bpermute((lane ^ mask) << 2, __float_as_int(v))); }
; __device__ __forceinline__ f32x4 mfma16(bf16x8 a, bf16x8 b, f32x4 c) { return __builtin_amdgcn_mfma_f32_16x16x32_bf16(a, b, c, 0, 0, 0); }
; #define A2_WRITEK(buf_) do { _Pragma("unroll") for (int j = 0; j < 8; ++j) *(LAS u32x4*)((buf_) + klo + j * (16 * 272)) = t8[j]; } while (0)
; template <bool NA> ...
;     ...
;         for (int ks = 0; ks < NSTEP; ++ks) {
;             LAS unsigned char* cur = lds + cb * ABUF2; LAS unsigned char* nxt = lds + (cb ^ 1) * ABUF2;
;             if (ks < NSTEP - 1) A2_LOADK(hp, ks + 1); else A2_LOADV(hp, 0);
;             SCHED_FENCE();
; #pragma unroll
;             for (int g = 0; g < NGRP; ++g) {
;                 const int gi = ks * NGRP + g, koff = NA ? g * 64 + w0 : g * 32;
;                 const LAS unsigned char* kp = cur + (hh * 128 + koff + fr) * 272 + fq * 16;
;                 bf16x8 kf[2][4];
; #pragma unroll
;                 for (int a = 0; a < 2; ++a)
; #pragma unroll
;                     for (int dc = 0; dc < 4; ++dc) kf[a][dc] = *(const LAS bf16x8*)(kp + a * 16 * 272 + dc * 64);
;                 f32x4 s0 = (f32x4){0.f, 0.f, 0.f, 0.f}, s1 = (f32x4){0.f, 0.f, 0.f, 0.f};
; #pragma unroll
;                 for (int dc = 0; dc < 4; ++dc) { s0 = mfma16(kf[0][dc], qf[dc], s0); s1 = mfma16(kf[1][dc], qf[dc], s1); }
;                 if (NA) { const LAS float* br = rpb + ((hp * 2 + hh) * 15 + brow0 + 2 * ks + g) * 32;
; #pragma unroll
;                     for (int e = 0; e < 4; ++e) { s0[e] += br[bidx[e]]; s1[e] += br[bidx[4 + e]]; } }
;                 sc[gi][0] = s0; sc[gi][1] = s1;
;             }
;             SCHED_FENCE();
;             if (ks < NSTEP - 1) A2_WRITEK(nxt); else A2_WRITEV(nxt);
;             __syncthreads(); cb ^= 1;
;         }
;         float mx = -3.0e38f;
; #pragma unroll
;         for (int gi = 0; gi < 8; ++gi)
; #pragma unroll
;             for (int a = 0; a < 2; ++a) mx = fmaxf(mx, fmaxf(fmaxf(sc[gi][a].x, sc[gi][a].y), fmaxf(sc[gi][a].z, sc[gi][a].w)));
;         mx = fmaxf(mx, shfl_xor_l(mx, lane, 16)); mx = fmaxf(mx, shfl_xor_l(mx, lane, 32));
	global_load_dwordx4 v[78:81], v[44:45], off
	global_load_dwordx4 v[82:85], v[46:47], off
	global_load_dwordx4 v[86:89], v[48:49], off
	global_load_dwordx4 v[168:171], v[50:51], off
	global_load_dwordx4 v[172:175], v[56:57], off
	global_load_dwordx4 v[176:179], v[58:59], off
	v_addc_co_u32_e32 v63, vcc, 0, v17, vcc
	global_load_dwordx4 v[180:183], v[60:61], off
	global_load_dwordx4 v[184:187], v[62:63], off
	ds_read_b128 v[188:191], v43
	ds_read_b128 v[192:195], v43 offset:64
	ds_read_b128 v[196:199], v43 offset:4352
	ds_read_b128 v[200:203], v43 offset:4416
	v_add_u32_e32 v16, 0x23680, v29
	v_add_u32_e32 v17, 0x23680, v35
	s_waitcnt lgkmcnt(3)
	v_mfma_f32_16x16x32_bf16 v[188:191], v[188:191], v[0:3], 0
	v_add_u32_e32 v42, 0x23680, v36
	v_add_u32_e32 v161, 0x23680, v37
	v_add_u32_e32 v208, 0x23680, v38
	s_waitcnt lgkmcnt(2)
	v_mfma_f32_16x16x32_bf16 v[188:191], v[192:195], v[4:7], v[188:191]
	ds_read_b128 v[192:195], v43 offset:128
	v_add_u32_e32 v209, 0x23680, v39
	v_add_u32_e32 v210, 0x23680, v41
	s_waitcnt lgkmcnt(2)
	v_mfma_f32_16x16x32_bf16 v[196:199], v[196:199], v[0:3], 0
	v_add_u32_e32 v211, 0x23680, v40
	v_add_u32_e32 v29, 0x23700, v29
	v_add_u32_e32 v35, 0x23700, v35
	s_waitcnt lgkmcnt(1)
	v_mfma_f32_16x16x32_bf16 v[196:199], v[200:203], v[4:7], v[196:199]
	ds_read_b128 v[200:203], v43 offset:4480
	ds_read_b128 v[204:207], v43 offset:192
	v_add_u32_e32 v41, 0x23700, v41
	v_add_u32_e32 v40, 0x23700, v40
	s_waitcnt lgkmcnt(2)
	v_mfma_f32_16x16x32_bf16 v[188:191], v[192:195], v[8:11], v[188:191]
	ds_read_b128 v[192:195], v43 offset:4544
	s_waitcnt lgkmcnt(2)
	v_mfma_f32_16x16x32_bf16 v[196:199], v[200:203], v[8:11], v[196:199]
	ds_read_b128 v[200:203], v43 offset:17408
	s_waitcnt lgkmcnt(2)
	v_mfma_f32_16x16x32_bf16 v[188:191], v[204:207], v[12:15], v[188:191]
	s_waitcnt lgkmcnt(1)
	v_mfma_f32_16x16x32_bf16 v[192:195], v[192:195], v[12:15], v[196:199]
	s_nop 2
	ds_read_b128 v[196:199], v43 offset:17472
	ds_read_b128 v[204:207], v43 offset:21760
	ds_read_b32 v16, v16
	ds_read_b32 v17, v17
	ds_read_b32 v42, v42
	ds_read_b32 v161, v161
	ds_read_b32 v233, v208
	ds_read_b32 v234, v209
	ds_read_b32 v235, v210
	ds_read_b32 v236, v211
	ds_read_b128 v[208:211], v43 offset:21824
	s_waitcnt lgkmcnt(11)
	v_mfma_f32_16x16x32_bf16 v[200:203], v[200:203], v[0:3], 0
	ds_read_b128 v[218:221], v43 offset:17536
	s_waitcnt lgkmcnt(9)
	v_add_f32_e32 v16, v188, v16
	s_waitcnt lgkmcnt(8)
	v_add_f32_e32 v17, v192, v17
	v_mfma_f32_16x16x32_bf16 v[204:207], v[204:207], v[0:3], 0
	s_waitcnt lgkmcnt(7)
	v_add_f32_e32 v237, v189, v42
	s_waitcnt lgkmcnt(6)
	v_add_f32_e32 v238, v193, v161
	s_waitcnt lgkmcnt(5)
	v_add_f32_e32 v233, v190, v233
	v_mfma_f32_16x16x32_bf16 v[196:199], v[196:199], v[4:7], v[200:203]
	v_add_u32_e32 v42, 0x23700, v36
	v_add_u32_e32 v161, 0x23700, v38
	s_nop 0
	ds_read_b128 v[200:203], v43 offset:21888
	s_waitcnt lgkmcnt(2)
	v_mfma_f32_16x16x32_bf16 v[204:207], v[208:211], v[4:7], v[204:207]
	v_add_f32_e32 v208, v194, v234
	v_add_f32_e32 v209, v191, v235
	ds_read_b128 v[188:191], v43 offset:17600
	v_add_f32_e32 v210, v195, v236
	ds_read_b128 v[192:195], v43 offset:21952
	s_waitcnt lgkmcnt(3)
	v_mfma_f32_16x16x32_bf16 v[196:199], v[218:221], v[8:11], v[196:199]
	v_add_u32_e32 v43, 0x23700, v37
	s_waitcnt lgkmcnt(2)
	v_mfma_f32_16x16x32_bf16 v[200:203], v[200:203], v[8:11], v[204:207]
	s_waitcnt lgkmcnt(1)
	v_mfma_f32_16x16x32_bf16 v[188:191], v[188:191], v[12:15], v[196:199]
	s_nop 2
	v_add_u32_e32 v196, 0x23700, v39
	s_waitcnt lgkmcnt(0)
	v_mfma_f32_16x16x32_bf16 v[36:39], v[192:195], v[12:15], v[200:203]
	ds_read_b32 v29, v29
	ds_read_b32 v35, v35
	ds_read_b32 v42, v42
	ds_read_b32 v43, v43
	ds_read_b32 v161, v161
	ds_read_b32 v192, v196
	ds_read_b32 v41, v41
	ds_read_b32 v40, v40
	s_waitcnt lgkmcnt(7)
	v_add_f32_e32 v188, v188, v29
	s_waitcnt lgkmcnt(5)
	v_add_f32_e32 v189, v189, v42
	v_add_f32_e32 v193, v36, v35
	s_waitcnt lgkmcnt(4)
	v_add_f32_e32 v194, v37, v43
	s_waitcnt lgkmcnt(3)
	v_add_f32_e32 v190, v190, v161
	s_waitcnt lgkmcnt(2)
	v_add_f32_e32 v192, v38, v192
	s_waitcnt lgkmcnt(1)
	v_add_f32_e32 v191, v191, v41
	s_waitcnt lgkmcnt(0)
	v_add_f32_e32 v195, v39, v40
	v_max_f32_e32 v29, v20, v19
	v_max_f32_e32 v35, v21, v18
	v_max3_f32 v29, v24, v25, v29
	v_max3_f32 v35, v22, v23, v35
	v_max3_f32 v29, v29, s27, v35
	v_max_f32_e32 v35, v30, v27
	v_max_f32_e32 v36, v28, v26
	v_max3_f32 v35, v34, v32, v35
	v_max3_f32 v36, v33, v31, v36
	v_max3_f32 v29, v29, v35, v36
	v_max_f32_e32 v35, v66, v67
	v_max_f32_e32 v36, v54, v55
	v_max3_f32 v35, v64, v65, v35
	v_max3_f32 v36, v52, v53, v36
	v_max3_f32 v29, v29, v35, v36
	v_max_f32_e32 v35, v71, v69
	v_max_f32_e32 v36, v70, v68
	v_max3_f32 v35, v75, v73, v35
	v_max3_f32 v36, v74, v72, v36
	v_max3_f32 v29, v29, v35, v36
	v_max_f32_e32 v35, v224, v225
	v_max_f32_e32 v36, v162, v226
	v_max3_f32 v35, v222, v90, v35
	v_max3_f32 v36, v223, v91, v36
	v_max3_f32 v29, v29, v35, v36
	v_max_f32_e32 v35, v231, v77
	v_max_f32_e32 v36, v232, v76
	v_max3_f32 v35, v227, v229, v35
	v_max3_f32 v36, v228, v230, v36
	v_max3_f32 v29, v29, v35, v36
	v_max_f32_e32 v35, v233, v209
	v_max_f32_e32 v36, v208, v210
	v_max3_f32 v35, v16, v237, v35
	v_max3_f32 v36, v17, v238, v36
	v_max3_f32 v29, v29, v35, v36
	v_max_f32_e32 v35, v190, v191
	v_max_f32_e32 v36, v192, v195
	v_max3_f32 v35, v188, v189, v35
	v_max3_f32 v36, v193, v194, v36
	v_max3_f32 v29, v29, v35, v36
	ds_bpermute_b32 v35, v156, v29
	v_add_u32_e32 v161, 0, v102
	s_waitcnt vmcnt(7)
	ds_write_b128 v161, v[78:81]
	s_waitcnt vmcnt(6)
	ds_write_b128 v161, v[82:85] offset:8704
	s_waitcnt vmcnt(5)
	ds_write_b128 v161, v[86:89] offset:17408
	s_waitcnt vmcnt(4)
	ds_write_b128 v161, v[168:171] offset:26112
	s_waitcnt vmcnt(3)
	ds_write_b128 v161, v[172:175] offset:34816
	s_waitcnt vmcnt(2)
	ds_write_b128 v161, v[176:179] offset:43520
	s_waitcnt vmcnt(1)
	ds_write_b128 v161, v[180:183] offset:52224
	s_waitcnt vmcnt(0)
	ds_write_b128 v161, v[184:187] offset:60928
	s_waitcnt lgkmcnt(8)
	v_max_f32_e32 v35, v35, v35
	v_max_f32_e32 v29, v29, v35
	ds_bpermute_b32 v35, v157, v29
	s_waitcnt lgkmcnt(0)
	s_barrier
; #define LAS __attribute__((address_space(3)))
; __device__ __forceinline__ unsigned pk2(float lo, float hi) { unsigned r; asm("v_cvt_pk_bf16_f32 %0, %1, %2" : "=v"(r) : "v"(lo), "v"(hi)); return r; }
; __device__ __forceinline__ float shfl_xor_l(float v, int lane, int mask) { return __int_as_float(__builtin_amdgcn_ds_bpermute((lane ^ mask) << 2, __float_as_int(v))); }
; __device__ __forceinline__ float fexp2(float x) { return __builtin_amdgcn_exp2f(x); }
; #define A2_LOADK(hp_, s_) do { const char* _g = (const char*)(kg0 + (size_t)(s_) * kstep + (hp_) * 256); _Pragma("unroll") for (int j = 0; j < 8; ++j) t8[j] = *(const u32x4*)(_g + (size_t)j * (16 * kld * 2) + kgo); } while (0)
; template <bool NA> ...
;     ...
;         float mx = -3.0e38f;
; #pragma unroll
;         for (int gi = 0; gi < 8; ++gi)
; #pragma unroll
;             for (int a = 0; a < 2; ++a) mx = fmaxf(mx, fmaxf(fmaxf(sc[gi][a].x, sc[gi][a].y), fmaxf(sc[gi][a].z, sc[gi][a].w)));
;         mx = fmaxf(mx, shfl_xor_l(mx, lane, 16)); mx = fmaxf(mx, shfl_xor_l(mx, lane, 32));
;         float l = 0.f; bf16x8 pb[8];
; #pragma unroll
;         for (int gi = 0; gi < 8; ++gi) {
;             f32x4 p0 = sc[gi][0], p1 = sc[gi][1];
; #pragma unroll
;             for (int e = 0; e < 4; ++e) { p0[e] = fexp2(p0[e] - mx); p1[e] = fexp2(p1[e] - mx); }
;             l += ((p0.x + p0.y) + (p0.z + p0.w)) + ((p1.x + p1.y) + (p1.z + p1.w));
;             u32x4 pw; pw.x = pk2(p0.x, p0.y); pw.y = pk2(p0.z, p0.w); pw.z = pk2(p1.x, p1.y); pw.w = pk2(p1.z, p1.w);
;             pb[gi] = __builtin_bit_cast(bf16x8, pw);
;         }
;         l += shfl_xor_l(l, lane, 16); l += shfl_xor_l(l, lane, 32);
;         f32x4 o[8];
; #pragma unroll
;         for (int d = 0; d < 8; ++d) o[d] = (f32x4){0.f, 0.f, 0.f, 0.f};
; #pragma unroll
;         for (int vs = 0; vs < NSTEP; ++vs) {
;             LAS unsigned char* cur = lds + cb * ABUF2; LAS unsigned char* nxt = lds + (cb ^ 1) * ABUF2;
;             if (vs == NSTEP - 1 && hp < NHP - 1) {
;                 const bf16_t* qa = qbase + ((hp + 1) * 2 + hh) * 128;
; #pragma unroll
;                 for (int dc = 0; dc < 4; ++dc) qfn[dc] = *(const bf16x8*)(qa + dc * 32);
;             }
;             if (vs < NSTEP - 1) A2_LOADV(hp, vs + 1); else if (hp < NHP - 1) A2_LOADK(hp + 1, 0);
	s_cmpk_lg_i32 s13, 0x2d00
	v_max_f32_e32 v35, v35, v35
	v_max_f32_e32 v168, v29, v35
	v_sub_f32_e32 v24, v24, v168
	v_sub_f32_e32 v25, v25, v168
	v_sub_f32_e32 v20, v20, v168
	v_sub_f32_e32 v19, v19, v168
	v_exp_f32_e32 v24, v24
	v_sub_f32_e32 v22, v22, v168
	v_exp_f32_e32 v25, v25
	v_sub_f32_e32 v23, v23, v168
	v_exp_f32_e32 v20, v20
	v_sub_f32_e32 v21, v21, v168
	v_exp_f32_e32 v19, v19
	v_sub_f32_e32 v18, v18, v168
	v_exp_f32_e32 v22, v22
	v_exp_f32_e32 v23, v23
	v_exp_f32_e32 v21, v21
	v_exp_f32_e32 v18, v18
	v_add_f32_e32 v29, v24, v25
	v_add_f32_e32 v35, v20, v19
	v_add_f32_e32 v29, v29, v35
	v_add_f32_e32 v35, v22, v23
	v_add_f32_e32 v36, v21, v18
	v_cvt_pk_bf16_f32 v40, v24, v25
	v_cvt_pk_bf16_f32 v41, v20, v19
	v_cvt_pk_bf16_f32 v42, v22, v23
	v_cvt_pk_bf16_f32 v43, v21, v18
	v_sub_f32_e32 v18, v34, v168
	v_sub_f32_e32 v20, v32, v168
	v_sub_f32_e32 v22, v30, v168
	v_sub_f32_e32 v24, v27, v168
	v_exp_f32_e32 v18, v18
	v_sub_f32_e32 v19, v33, v168
	v_exp_f32_e32 v20, v20
	v_sub_f32_e32 v21, v31, v168
	v_exp_f32_e32 v22, v22
	v_sub_f32_e32 v23, v28, v168
	v_exp_f32_e32 v24, v24
	v_sub_f32_e32 v25, v26, v168
	v_exp_f32_e32 v19, v19
	v_exp_f32_e32 v21, v21
	v_exp_f32_e32 v23, v23
	v_exp_f32_e32 v25, v25
	v_add_f32_e32 v35, v35, v36
	v_add_f32_e32 v26, v18, v20
	v_add_f32_e32 v27, v22, v24
	v_cvt_pk_bf16_f32 v36, v18, v20
	v_cvt_pk_bf16_f32 v37, v22, v24
	v_sub_f32_e32 v18, v64, v168
	v_sub_f32_e32 v20, v65, v168
	v_sub_f32_e32 v22, v66, v168
	v_sub_f32_e32 v24, v67, v168
	v_add_f32_e32 v26, v26, v27
	v_add_f32_e32 v27, v19, v21
	v_add_f32_e32 v28, v23, v25
	v_cvt_pk_bf16_f32 v38, v19, v21
	v_cvt_pk_bf16_f32 v39, v23, v25
	v_exp_f32_e32 v18, v18
	v_sub_f32_e32 v19, v52, v168
	v_exp_f32_e32 v20, v20
	v_sub_f32_e32 v21, v53, v168
	v_exp_f32_e32 v22, v22
	v_sub_f32_e32 v23, v54, v168
	v_exp_f32_e32 v24, v24
	v_sub_f32_e32 v25, v55, v168
	v_exp_f32_e32 v19, v19
	v_exp_f32_e32 v21, v21
	v_exp_f32_e32 v23, v23
	v_exp_f32_e32 v25, v25
	v_add_f32_e32 v29, v29, v35
	v_add_f32_e32 v27, v27, v28
	v_add_f32_e32 v29, 0, v29
	v_add_f32_e32 v26, v26, v27
	v_add_f32_e32 v27, v18, v20
	v_add_f32_e32 v28, v22, v24
	v_add_f32_e32 v26, v26, v29
	v_add_f32_e32 v27, v27, v28
	v_add_f32_e32 v28, v19, v21
	v_add_f32_e32 v29, v23, v25
	v_cvt_pk_bf16_f32 v32, v18, v20
	v_cvt_pk_bf16_f32 v33, v22, v24
	v_cvt_pk_bf16_f32 v34, v19, v21
	v_cvt_pk_bf16_f32 v35, v23, v25
	v_sub_f32_e32 v18, v75, v168
	v_sub_f32_e32 v19, v74, v168
	v_sub_f32_e32 v20, v73, v168
	v_sub_f32_e32 v21, v72, v168
	v_sub_f32_e32 v22, v71, v168
	v_sub_f32_e32 v23, v70, v168
	v_sub_f32_e32 v24, v69, v168
	v_sub_f32_e32 v25, v68, v168
	global_load_dwordx4 v[64:67], v[44:45], off offset:256
	global_load_dwordx4 v[68:71], v[46:47], off offset:256
	global_load_dwordx4 v[72:75], v[48:49], off offset:256
	global_load_dwordx4 v[78:81], v[50:51], off offset:256
	global_load_dwordx4 v[82:85], v[56:57], off offset:256
	global_load_dwordx4 v[86:89], v[58:59], off offset:256
	global_load_dwordx4 v[170:173], v[60:61], off offset:256
	global_load_dwordx4 v[174:177], v[62:63], off offset:256
	v_exp_f32_e32 v18, v18
	v_exp_f32_e32 v20, v20
	v_exp_f32_e32 v22, v22
	v_exp_f32_e32 v24, v24
	v_exp_f32_e32 v19, v19
	v_exp_f32_e32 v21, v21
	v_exp_f32_e32 v23, v23
	v_exp_f32_e32 v25, v25
	v_add_f32_e32 v28, v28, v29
	v_add_f32_e32 v27, v27, v28
	v_add_f32_e32 v26, v27, v26
	v_add_f32_e32 v27, v18, v20
	v_add_f32_e32 v28, v22, v24
	v_add_f32_e32 v27, v27, v28
	v_add_f32_e32 v28, v19, v21
	v_add_f32_e32 v29, v23, v25
	v_add_f32_e32 v28, v28, v29
	v_add_f32_e32 v27, v27, v28
	v_cvt_pk_bf16_f32 v28, v18, v20
	v_cvt_pk_bf16_f32 v29, v22, v24
	v_sub_f32_e32 v18, v222, v168
	v_sub_f32_e32 v20, v90, v168
	v_sub_f32_e32 v22, v224, v168
	v_sub_f32_e32 v24, v225, v168
	v_cvt_pk_bf16_f32 v30, v19, v21
	v_cvt_pk_bf16_f32 v31, v23, v25
	v_exp_f32_e32 v18, v18
	v_sub_f32_e32 v19, v223, v168
	v_exp_f32_e32 v20, v20
	v_sub_f32_e32 v21, v91, v168
	v_exp_f32_e32 v22, v22
	v_sub_f32_e32 v23, v162, v168
	v_exp_f32_e32 v25, v24
	v_sub_f32_e32 v24, v226, v168
	v_add_f32_e32 v26, v27, v26
	v_exp_f32_e32 v19, v19
	v_exp_f32_e32 v21, v21
	v_exp_f32_e32 v23, v23
	v_exp_f32_e32 v27, v24
	v_add_f32_e32 v24, v18, v20
	v_add_f32_e32 v52, v22, v25
	v_add_f32_e32 v24, v24, v52
	v_add_f32_e32 v52, v19, v21
	v_add_f32_e32 v53, v23, v27
	v_add_f32_e32 v52, v52, v53
	v_add_f32_e32 v24, v24, v52
	v_add_f32_e32 v52, v24, v26
	v_cvt_pk_bf16_f32 v24, v18, v20
	v_cvt_pk_bf16_f32 v25, v22, v25
	v_sub_f32_e32 v18, v227, v168
	v_sub_f32_e32 v20, v229, v168
	v_sub_f32_e32 v22, v231, v168
	v_sub_f32_e32 v53, v77, v168
	v_cvt_pk_bf16_f32 v26, v19, v21
	v_cvt_pk_bf16_f32 v27, v23, v27
	v_exp_f32_e32 v18, v18
	v_sub_f32_e32 v19, v228, v168
	v_exp_f32_e32 v20, v20
	v_sub_f32_e32 v21, v230, v168
	v_exp_f32_e32 v22, v22
	v_sub_f32_e32 v23, v232, v168
	v_exp_f32_e32 v53, v53
	v_sub_f32_e32 v54, v76, v168
	v_exp_f32_e32 v19, v19
	v_exp_f32_e32 v21, v21
	v_exp_f32_e32 v23, v23
	v_exp_f32_e32 v55, v54
	v_add_f32_e32 v54, v18, v20
	v_add_f32_e32 v76, v22, v53
	v_add_f32_e32 v54, v54, v76
	v_add_f32_e32 v76, v19, v21
	v_add_f32_e32 v77, v23, v55
	v_add_f32_e32 v76, v76, v77
	v_add_f32_e32 v54, v54, v76
	v_add_f32_e32 v76, v54, v52
	v_cvt_pk_bf16_f32 v52, v18, v20
	v_sub_f32_e32 v20, v233, v168
	v_cvt_pk_bf16_f32 v54, v19, v21
	v_exp_f32_e32 v21, v20
	v_sub_f32_e32 v20, v208, v168
	v_cvt_pk_bf16_f32 v55, v23, v55
	v_sub_f32_e32 v16, v16, v168
	v_sub_f32_e32 v18, v237, v168
	v_exp_f32_e32 v23, v20
	v_sub_f32_e32 v20, v209, v168
	v_cvt_pk_bf16_f32 v53, v22, v53
	v_exp_f32_e32 v16, v16
	v_sub_f32_e32 v17, v17, v168
	v_exp_f32_e32 v18, v18
	v_sub_f32_e32 v19, v238, v168
	v_exp_f32_e32 v22, v20
	v_sub_f32_e32 v20, v210, v168
	v_exp_f32_e32 v17, v17
	v_exp_f32_e32 v19, v19
	v_exp_f32_e32 v77, v20
	v_add_f32_e32 v20, v16, v18
	v_add_f32_e32 v90, v21, v22
	v_add_f32_e32 v20, v20, v90
	v_add_f32_e32 v90, v17, v19
	v_add_f32_e32 v91, v23, v77
	v_add_f32_e32 v90, v90, v91
	v_add_f32_e32 v20, v20, v90
	v_cvt_pk_bf16_f32 v21, v21, v22
	v_cvt_pk_bf16_f32 v22, v17, v19
	v_sub_f32_e32 v17, v193, v168
	v_add_f32_e32 v76, v20, v76
	v_cvt_pk_bf16_f32 v20, v16, v18
	v_sub_f32_e32 v16, v188, v168
	v_exp_f32_e32 v18, v17
	v_sub_f32_e32 v17, v189, v168
	v_sub_f32_e32 v90, v190, v168
	v_sub_f32_e32 v162, v191, v168
	v_exp_f32_e32 v16, v16
	v_exp_f32_e32 v17, v17
	v_sub_f32_e32 v19, v194, v168
	v_exp_f32_e32 v90, v90
	v_sub_f32_e32 v91, v192, v168
	v_exp_f32_e32 v162, v162
	v_sub_f32_e32 v168, v195, v168
	v_exp_f32_e32 v19, v19
	v_exp_f32_e32 v91, v91
	v_exp_f32_e32 v178, v168
	v_add_f32_e32 v168, v16, v17
	v_add_f32_e32 v169, v90, v162
	v_add_f32_e32 v168, v168, v169
	v_add_f32_e32 v169, v18, v19
	v_add_f32_e32 v179, v91, v178
	v_add_f32_e32 v169, v169, v179
	v_add_f32_e32 v168, v168, v169
	v_add_f32_e32 v76, v168, v76
	ds_bpermute_b32 v168, v156, v76
	s_cselect_b64 s[8:9], -1, 0
	v_cvt_pk_bf16_f32 v23, v23, v77
	v_cvt_pk_bf16_f32 v16, v16, v17
	v_cvt_pk_bf16_f32 v17, v90, v162
	s_waitcnt lgkmcnt(0)
; #define LAS __attribute__((address_space(3)))
; #define SCHED_FENCE() __builtin_amdgcn_sched_barrier(0)
; __device__ __forceinline__ unsigned pk2(float lo, float hi) { unsigned r; asm("v_cvt_pk_bf16_f32 %0, %1, %2" : "=v"(r) : "v"(lo), "v"(hi)); return r; }
; __device__ __forceinline__ float fexp2(float x) { return __builtin_amdgcn_exp2f(x); }
; template <bool NA> ...
;     ...
;         for (int gi = 0; gi < 8; ++gi) {
;             f32x4 p0 = sc[gi][0], p1 = sc[gi][1];
; #pragma unroll
;             for (int e = 0; e < 4; ++e) { p0[e] = fexp2(p0[e] - mx); p1[e] = fexp2(p1[e] - mx); }
;             l += ((p0.x + p0.y) + (p0.z + p0.w)) + ((p1.x + p1.y) + (p1.z + p1.w));
;             u32x4 pw; pw.x = pk2(p0.x, p0.y); pw.y = pk2(p0.z, p0.w); pw.z = pk2(p1.x, p1.y); pw.w = pk2(p1.z, p1.w);
;             pb[gi] = __builtin_bit_cast(bf16x8, pw);
;         }
;         l += shfl_xor_l(l, lane, 16); l += shfl_xor_l(l, lane, 32);
;         f32x4 o[8];
; #pragma unroll
;         for (int d = 0; d < 8; ++d) o[d] = (f32x4){0.f, 0.f, 0.f, 0.f};
; #pragma unroll
;         for (int vs = 0; vs < NSTEP; ++vs) {
;             LAS unsigned char* cur = lds + cb * ABUF2; LAS unsigned char* nxt = lds + (cb ^ 1) * ABUF2;
;             if (vs == NSTEP - 1 && hp < NHP - 1) {
;                 const bf16_t* qa = qbase + ((hp + 1) * 2 + hh) * 128;
; #pragma unroll
;                 for (int dc = 0; dc < 4; ++dc) qfn[dc] = *(const bf16x8*)(qa + dc * 32);
;             }
;             if (vs < NSTEP - 1) A2_LOADV(hp, vs + 1); else if (hp < NHP - 1) A2_LOADK(hp + 1, 0);
;             SCHED_FENCE();
; #pragma unroll
;             for (int g = 0; g < NGRP; ++g) {
;                 const int gi = vs * NGRP + g, voff = NA ? g * 64 + w0 : g * 32;
;                 const LAS unsigned char* vp = cur + (hh * 128 + fr) * 272 + (voff + fq * 4) * 2;
; #pragma unroll
;                 for (int d = 0; d < 8; ++d) {
;                     const u32x2 lo = *(const LAS u32x2*)(vp + d * 16 * 272), hi = *(const LAS u32x2*)(vp + d * 16 * 272 + 32);
;                     u32x4 vw; vw.x = lo.x; vw.y = lo.y; vw.z = hi.x; vw.w = hi.y;
;                     o[d] = mfma16(__builtin_bit_cast(bf16x8, vw), pb[gi], o[d]);
;                 }
;             }
;             SCHED_FENCE();
;             if (vs < NSTEP - 1) A2_WRITEV(nxt); else if (hp < NHP - 1) A2_WRITEK(nxt);
;             __syncthreads(); cb ^= 1;
	v_add_f32_e32 v168, v76, v168
	ds_bpermute_b32 v169, v157, v168
	v_cvt_pk_bf16_f32 v18, v18, v19
	v_cvt_pk_bf16_f32 v19, v91, v178
	s_cmpk_eq_i32 s13, 0x2d00
	v_add_u32_e32 v210, 0x1000, v103
	v_add_u32_e32 v211, 0x2000, v103
	v_add_u32_e32 v218, 0x3000, v103
	v_add_u32_e32 v219, 0x4000, v103
	v_add_u32_e32 v220, 0x5000, v103
	v_add_u32_e32 v221, 0x6000, v103
	v_add_u32_e32 v222, 0x7000, v103
	ds_read2_b64 v[178:181], v103 offset1:4
	ds_read2_b64 v[182:185], v210 offset0:32 offset1:36
	ds_read2_b64 v[186:189], v211 offset0:64 offset1:68
	ds_read2_b64 v[190:193], v218 offset0:96 offset1:100
	ds_read2_b64 v[194:197], v219 offset0:128 offset1:132
	ds_read2_b64 v[198:201], v220 offset0:160 offset1:164
	ds_read2_b64 v[202:205], v221 offset0:192 offset1:196
	ds_read2_b64 v[206:209], v222 offset0:224 offset1:228
	s_waitcnt lgkmcnt(7)
	v_mfma_f32_16x16x32_bf16 v[178:181], v[178:181], v[40:43], 0
	s_waitcnt lgkmcnt(6)
	v_mfma_f32_16x16x32_bf16 v[182:185], v[182:185], v[40:43], 0
	s_waitcnt lgkmcnt(5)
	v_mfma_f32_16x16x32_bf16 v[186:189], v[186:189], v[40:43], 0
	s_waitcnt lgkmcnt(4)
	v_mfma_f32_16x16x32_bf16 v[190:193], v[190:193], v[40:43], 0
	s_waitcnt lgkmcnt(3)
	v_mfma_f32_16x16x32_bf16 v[194:197], v[194:197], v[40:43], 0
	s_waitcnt lgkmcnt(2)
	v_mfma_f32_16x16x32_bf16 v[198:201], v[198:201], v[40:43], 0
	s_waitcnt lgkmcnt(1)
	v_mfma_f32_16x16x32_bf16 v[202:205], v[202:205], v[40:43], 0
	s_waitcnt lgkmcnt(0)
	v_mfma_f32_16x16x32_bf16 v[40:43], v[206:209], v[40:43], 0
	ds_read2_b64 v[240:243], v103 offset0:16 offset1:20
	ds_read2_b64 v[244:247], v210 offset0:48 offset1:52
	s_waitcnt lgkmcnt(1)
	v_mfma_f32_16x16x32_bf16 v[178:181], v[240:243], v[36:39], v[178:181]
	ds_read2_b64 v[240:243], v211 offset0:80 offset1:84
	s_waitcnt lgkmcnt(1)
	v_mfma_f32_16x16x32_bf16 v[182:185], v[244:247], v[36:39], v[182:185]
	ds_read2_b64 v[244:247], v218 offset0:112 offset1:116
	s_waitcnt lgkmcnt(1)
	v_mfma_f32_16x16x32_bf16 v[186:189], v[240:243], v[36:39], v[186:189]
	ds_read2_b64 v[240:243], v219 offset0:144 offset1:148
	s_waitcnt lgkmcnt(1)
	v_mfma_f32_16x16x32_bf16 v[190:193], v[244:247], v[36:39], v[190:193]
	ds_read2_b64 v[244:247], v220 offset0:176 offset1:180
	s_waitcnt lgkmcnt(1)
	v_mfma_f32_16x16x32_bf16 v[194:197], v[240:243], v[36:39], v[194:197]
	ds_read2_b64 v[240:243], v221 offset0:208 offset1:212
	s_waitcnt lgkmcnt(1)
	v_mfma_f32_16x16x32_bf16 v[198:201], v[244:247], v[36:39], v[198:201]
	s_waitcnt lgkmcnt(0)
	v_mfma_f32_16x16x32_bf16 v[202:205], v[240:243], v[36:39], v[202:205]
	ds_read2_b64 v[206:209], v222 offset0:240 offset1:244
	s_waitcnt lgkmcnt(0)
	v_mfma_f32_16x16x32_bf16 v[36:39], v[206:209], v[36:39], v[40:43]
	v_add_u32_e32 v162, s7, v102
	s_waitcnt vmcnt(7)
	ds_write_b128 v162, v[64:67]
	s_waitcnt vmcnt(6)
	ds_write_b128 v162, v[68:71] offset:8704
	s_waitcnt vmcnt(5)
	ds_write_b128 v162, v[72:75] offset:17408
	s_waitcnt vmcnt(4)
	ds_write_b128 v162, v[78:81] offset:26112
	s_waitcnt vmcnt(3)
	ds_write_b128 v162, v[82:85] offset:34816
	s_waitcnt vmcnt(2)
	ds_write_b128 v162, v[86:89] offset:43520
	s_waitcnt vmcnt(1)
	ds_write_b128 v162, v[170:173] offset:52224
	s_waitcnt vmcnt(0)
	ds_write_b128 v162, v[174:177] offset:60928
	s_waitcnt lgkmcnt(0)
	s_barrier
	global_load_dwordx4 v[40:43], v[44:45], off offset:512
	global_load_dwordx4 v[64:67], v[46:47], off offset:512
	global_load_dwordx4 v[68:71], v[48:49], off offset:512
	global_load_dwordx4 v[72:75], v[50:51], off offset:512
	global_load_dwordx4 v[76:79], v[56:57], off offset:512
	global_load_dwordx4 v[80:83], v[58:59], off offset:512
	global_load_dwordx4 v[84:87], v[60:61], off offset:512
	global_load_dwordx4 v[88:91], v[62:63], off offset:512
	ds_read_b64 v[170:171], v118
	ds_read_b64 v[172:173], v119
	ds_read_b64 v[174:175], v120
	ds_read_b64 v[176:177], v121
	s_waitcnt lgkmcnt(2)
	v_mfma_f32_16x16x32_bf16 v[170:173], v[170:173], v[32:35], v[178:181]
	s_nop 2
	ds_read_b64 v[178:179], v122
	ds_read_b64 v[180:181], v123
	s_waitcnt lgkmcnt(2)
	v_mfma_f32_16x16x32_bf16 v[174:177], v[174:177], v[32:35], v[182:185]
	s_nop 2
	ds_read_b64 v[182:183], v124
	ds_read_b64 v[184:185], v125
	s_waitcnt lgkmcnt(2)
	v_mfma_f32_16x16x32_bf16 v[178:181], v[178:181], v[32:35], v[186:189]
	s_nop 2
	ds_read_b64 v[186:187], v126
	ds_read_b64 v[188:189], v127
	s_waitcnt lgkmcnt(2)
	v_mfma_f32_16x16x32_bf16 v[182:185], v[182:185], v[32:35], v[190:193]
	s_nop 2
	ds_read_b64 v[190:191], v128
	ds_read_b64 v[192:193], v129
	s_waitcnt lgkmcnt(2)
	v_mfma_f32_16x16x32_bf16 v[186:189], v[186:189], v[32:35], v[194:197]
	s_nop 2
	ds_read_b64 v[194:195], v130
	ds_read_b64 v[196:197], v131
	s_waitcnt lgkmcnt(2)
	v_mfma_f32_16x16x32_bf16 v[190:193], v[190:193], v[32:35], v[198:201]
	s_nop 2
	ds_read_b64 v[198:199], v132
	ds_read_b64 v[200:201], v133
	s_waitcnt lgkmcnt(2)
	v_mfma_f32_16x16x32_bf16 v[194:197], v[194:197], v[32:35], v[202:205]
	s_waitcnt lgkmcnt(0)
	v_mfma_f32_16x16x32_bf16 v[32:35], v[198:201], v[32:35], v[36:39]
	s_nop 2
	ds_read_b64 v[240:241], v134
	ds_read_b64 v[242:243], v135
	ds_read_b64 v[244:245], v136
	ds_read_b64 v[246:247], v137
	s_waitcnt lgkmcnt(2)
	v_mfma_f32_16x16x32_bf16 v[170:173], v[240:243], v[28:31], v[170:173]
	ds_read_b64 v[240:241], v138
	ds_read_b64 v[242:243], v139
	s_waitcnt lgkmcnt(2)
	v_mfma_f32_16x16x32_bf16 v[174:177], v[244:247], v[28:31], v[174:177]
	ds_read_b64 v[244:245], v140
	ds_read_b64 v[246:247], v141
	s_waitcnt lgkmcnt(2)
	v_mfma_f32_16x16x32_bf16 v[178:181], v[240:243], v[28:31], v[178:181]
	ds_read_b64 v[240:241], v142
	ds_read_b64 v[242:243], v143
	s_waitcnt lgkmcnt(2)
	v_mfma_f32_16x16x32_bf16 v[182:185], v[244:247], v[28:31], v[182:185]
	ds_read_b64 v[244:245], v146
	ds_read_b64 v[246:247], v147
	s_waitcnt lgkmcnt(2)
	v_mfma_f32_16x16x32_bf16 v[186:189], v[240:243], v[28:31], v[186:189]
	ds_read_b64 v[240:241], v148
	ds_read_b64 v[242:243], v149
	s_waitcnt lgkmcnt(2)
	v_mfma_f32_16x16x32_bf16 v[190:193], v[244:247], v[28:31], v[190:193]
	ds_read_b64 v[244:245], v150
	ds_read_b64 v[246:247], v151
	s_waitcnt lgkmcnt(2)
	v_mfma_f32_16x16x32_bf16 v[194:197], v[240:243], v[28:31], v[194:197]
	s_waitcnt lgkmcnt(0)
	v_mfma_f32_16x16x32_bf16 v[198:201], v[244:247], v[28:31], v[32:35]
	s_waitcnt vmcnt(7)
	ds_write_b128 v161, v[40:43]
	s_waitcnt vmcnt(6)
	ds_write_b128 v161, v[64:67] offset:8704
	s_waitcnt vmcnt(5)
	ds_write_b128 v161, v[68:71] offset:17408
	s_waitcnt vmcnt(4)
	ds_write_b128 v161, v[72:75] offset:26112
	s_waitcnt vmcnt(3)
	ds_write_b128 v161, v[76:79] offset:34816
	s_waitcnt vmcnt(2)
	ds_write_b128 v161, v[80:83] offset:43520
	s_waitcnt vmcnt(1)
	ds_write_b128 v161, v[84:87] offset:52224
	s_waitcnt vmcnt(0)
	ds_write_b128 v161, v[88:91] offset:60928
	s_waitcnt lgkmcnt(0)
	s_barrier
; #define LAS __attribute__((address_space(3)))
; #define SCHED_FENCE() __builtin_amdgcn_sched_barrier(0)
; __device__ __forceinline__ f32x4 mfma16(bf16x8 a, bf16x8 b, f32x4 c) { return __builtin_amdgcn_mfma_f32_16x16x32_bf16(a, b, c, 0, 0, 0); }
; #define A2_LOADK(hp_, s_) do { const char* _g = (const char*)(kg0 + (size_t)(s_) * kstep + (hp_) * 256); _Pragma("unroll") for (int j = 0; j < 8; ++j) t8[j] = *(const u32x4*)(_g + (size_t)j * (16 * kld * 2) + kgo); } while (0)
; #define A2_LOADV(hp_, s_) do { const char* _g = (const char*)(vg0 + (size_t)(hp_) * 256 * vld + (size_t)(s_) * vstep); _Pragma("unroll") for (int j = 0; j < 8; ++j) t8[j] = *(const u32x4*)(_g + (size_t)j * (32 * vld * 2) + vgo); } while (0)
; #define A2_WRITEK(buf_) do { _Pragma("unroll") for (int j = 0; j < 8; ++j) *(LAS u32x4*)((buf_) + klo + j * (16 * 272)) = t8[j]; } while (0)
; #define A2_WRITEV(buf_) do { _Pragma("unroll") for (int j = 0; j < 8; ++j) *(LAS u32x4*)((buf_) + vlo + j * (32 * 272)) = t8[j]; } while (0)
; template <bool NA> ...
;     ...
;         for (int vs = 0; vs < NSTEP; ++vs) {
;             LAS unsigned char* cur = lds + cb * ABUF2; LAS unsigned char* nxt = lds + (cb ^ 1) * ABUF2;
;             if (vs == NSTEP - 1 && hp < NHP - 1) {
;                 const bf16_t* qa = qbase + ((hp + 1) * 2 + hh) * 128;
; #pragma unroll
;                 for (int dc = 0; dc < 4; ++dc) qfn[dc] = *(const bf16x8*)(qa + dc * 32);
;             }
;             if (vs < NSTEP - 1) A2_LOADV(hp, vs + 1); else if (hp < NHP - 1) A2_LOADK(hp + 1, 0);
;             SCHED_FENCE();
; #pragma unroll
;             for (int g = 0; g < NGRP; ++g) {
;                 const int gi = vs * NGRP + g, voff = NA ? g * 64 + w0 : g * 32;
;                 const LAS unsigned char* vp = cur + (hh * 128 + fr) * 272 + (voff + fq * 4) * 2;
; #pragma unroll
;                 for (int d = 0; d < 8; ++d) {
;                     const u32x2 lo = *(const LAS u32x2*)(vp + d * 16 * 272), hi = *(const LAS u32x2*)(vp + d * 16 * 272 + 32);
;                     u32x4 vw; vw.x = lo.x; vw.y = lo.y; vw.z = hi.x; vw.w = hi.y;
;                     o[d] = mfma16(__builtin_bit_cast(bf16x8, vw), pb[gi], o[d]);
;                 }
;             }
;             SCHED_FENCE();
;             if (vs < NSTEP - 1) A2_WRITEV(nxt); else if (hp < NHP - 1) A2_WRITEK(nxt);
;             __syncthreads(); cb ^= 1;
	global_load_dwordx4 v[32:35], v[44:45], off offset:768
	global_load_dwordx4 v[28:31], v[46:47], off offset:768
	global_load_dwordx4 v[40:43], v[48:49], off offset:768
	global_load_dwordx4 v[36:39], v[50:51], off offset:768
	s_nop 0
	global_load_dwordx4 v[48:51], v[56:57], off offset:768
	global_load_dwordx4 v[44:47], v[58:59], off offset:768
	s_nop 0
	global_load_dwordx4 v[56:59], v[60:61], off offset:768
	s_nop 0
	global_load_dwordx4 v[60:63], v[62:63], off offset:768
	ds_read2_b64 v[64:67], v103 offset1:4
	ds_read2_b64 v[80:83], v219 offset0:128 offset1:132
	ds_read2_b64 v[68:71], v210 offset0:32 offset1:36
	ds_read2_b64 v[72:75], v211 offset0:64 offset1:68
	ds_read2_b64 v[76:79], v218 offset0:96 offset1:100
	s_waitcnt lgkmcnt(4)
	v_mfma_f32_16x16x32_bf16 v[64:67], v[64:67], v[24:27], v[170:173]
	s_waitcnt lgkmcnt(3)
	v_mfma_f32_16x16x32_bf16 v[170:173], v[80:83], v[24:27], v[186:189]
	ds_read2_b64 v[80:83], v220 offset0:160 offset1:164
	s_waitcnt lgkmcnt(3)
	v_mfma_f32_16x16x32_bf16 v[68:71], v[68:71], v[24:27], v[174:177]
	s_waitcnt lgkmcnt(0)
	v_mfma_f32_16x16x32_bf16 v[174:177], v[80:83], v[24:27], v[190:193]
	ds_read2_b64 v[80:83], v221 offset0:192 offset1:196
	v_mfma_f32_16x16x32_bf16 v[72:75], v[72:75], v[24:27], v[178:181]
	s_waitcnt lgkmcnt(0)
	v_mfma_f32_16x16x32_bf16 v[178:181], v[80:83], v[24:27], v[194:197]
	ds_read2_b64 v[80:83], v222 offset0:224 offset1:228
	v_mfma_f32_16x16x32_bf16 v[76:79], v[76:79], v[24:27], v[182:185]
	s_waitcnt lgkmcnt(0)
	v_mfma_f32_16x16x32_bf16 v[24:27], v[80:83], v[24:27], v[198:201]
	ds_read2_b64 v[240:243], v103 offset0:16 offset1:20
	ds_read2_b64 v[244:247], v210 offset0:48 offset1:52
	s_waitcnt lgkmcnt(1)
	v_mfma_f32_16x16x32_bf16 v[88:91], v[240:243], v[52:55], v[64:67]
	ds_read2_b64 v[240:243], v211 offset0:80 offset1:84
	s_waitcnt lgkmcnt(1)
	v_mfma_f32_16x16x32_bf16 v[84:87], v[244:247], v[52:55], v[68:71]
	ds_read2_b64 v[244:247], v218 offset0:112 offset1:116
	s_waitcnt lgkmcnt(1)
	v_mfma_f32_16x16x32_bf16 v[80:83], v[240:243], v[52:55], v[72:75]
	ds_read2_b64 v[240:243], v219 offset0:144 offset1:148
	s_waitcnt lgkmcnt(1)
	v_mfma_f32_16x16x32_bf16 v[76:79], v[244:247], v[52:55], v[76:79]
	s_waitcnt lgkmcnt(0)
	v_mfma_f32_16x16x32_bf16 v[72:75], v[240:243], v[52:55], v[170:173]
	ds_read2_b64 v[64:67], v220 offset0:176 offset1:180
	s_nop 1
	ds_read2_b64 v[170:173], v222 offset0:240 offset1:244
	s_waitcnt lgkmcnt(1)
	v_mfma_f32_16x16x32_bf16 v[68:71], v[64:67], v[52:55], v[174:177]
	ds_read2_b64 v[64:67], v221 offset0:208 offset1:212
	s_waitcnt lgkmcnt(0)
	v_mfma_f32_16x16x32_bf16 v[64:67], v[64:67], v[52:55], v[178:181]
	v_mfma_f32_16x16x32_bf16 v[24:27], v[170:173], v[52:55], v[24:27]
	s_waitcnt vmcnt(7)
	ds_write_b128 v162, v[32:35]
	s_waitcnt vmcnt(6)
	ds_write_b128 v162, v[28:31] offset:8704
	s_waitcnt vmcnt(5)
	ds_write_b128 v162, v[40:43] offset:17408
	s_waitcnt vmcnt(4)
	ds_write_b128 v162, v[36:39] offset:26112
	s_waitcnt vmcnt(3)
	ds_write_b128 v162, v[48:51] offset:34816
	s_waitcnt vmcnt(2)
	ds_write_b128 v162, v[44:47] offset:43520
	s_waitcnt vmcnt(1)
	ds_write_b128 v162, v[56:59] offset:52224
	s_waitcnt vmcnt(0)
	ds_write_b128 v162, v[60:63] offset:60928
	s_waitcnt lgkmcnt(0)
	s_barrier
	s_cbranch_scc1 .LBB0_223
	v_lshl_add_u64 v[12:13], s[0:1], 0, v[110:111]
	global_load_dwordx4 v[0:3], v[12:13], off offset:-128
	global_load_dwordx4 v[4:7], v[12:13], off offset:-64
	global_load_dwordx4 v[8:11], v[12:13], off
	s_nop 0
	global_load_dwordx4 v[12:15], v[12:13], off offset:64

; #define LAS __attribute__((address_space(3)))
; #define SCHED_FENCE() __builtin_amdgcn_sched_barrier(0)
; __device__ __forceinline__ f32x4 mfma16(bf16x8 a, bf16x8 b, f32x4 c) { return __builtin_amdgcn_mfma_f32_16x16x32_bf16(a, b, c, 0, 0, 0); }
; #define A2_LOADK(hp_, s_) do { const char* _g = (const char*)(kg0 + (size_t)(s_) * kstep + (hp_) * 256); _Pragma("unroll") for (int j = 0; j < 8; ++j) t8[j] = *(const u32x4*)(_g + (size_t)j * (16 * kld * 2) + kgo); } while (0)
; #define A2_LOADV(hp_, s_) do { const char* _g = (const char*)(vg0 + (size_t)(hp_) * 256 * vld + (size_t)(s_) * vstep); _Pragma("unroll") for (int j = 0; j < 8; ++j) t8[j] = *(const u32x4*)(_g + (size_t)j * (32 * vld * 2) + vgo); } while (0)
; #define A2_WRITEK(buf_) do { _Pragma("unroll") for (int j = 0; j < 8; ++j) *(LAS u32x4*)((buf_) + klo + j * (16 * 272)) = t8[j]; } while (0)
; template <bool NA> ...
;     ...
;         for (int ks = 0; ks < NSTEP; ++ks) {
;             LAS unsigned char* cur = lds + cb * ABUF2; LAS unsigned char* nxt = lds + (cb ^ 1) * ABUF2;
;             if (ks < NSTEP - 1) A2_LOADK(hp, ks + 1); else A2_LOADV(hp, 0);
;             SCHED_FENCE();
; #pragma unroll
;             for (int g = 0; g < NGRP; ++g) {
;                 const int gi = ks * NGRP + g, koff = NA ? g * 64 + w0 : g * 32;
;                 const LAS unsigned char* kp = cur + (hh * 128 + koff + fr) * 272 + fq * 16;
;                 bf16x8 kf[2][4];
; #pragma unroll
;                 for (int a = 0; a < 2; ++a)
; #pragma unroll
;                     for (int dc = 0; dc < 4; ++dc) kf[a][dc] = *(const LAS bf16x8*)(kp + a * 16 * 272 + dc * 64);
;                 f32x4 s0 = (f32x4){0.f, 0.f, 0.f, 0.f}, s1 = (f32x4){0.f, 0.f, 0.f, 0.f};
; #pragma unroll
;                 for (int dc = 0; dc < 4; ++dc) { s0 = mfma16(kf[0][dc], qf[dc], s0); s1 = mfma16(kf[1][dc], qf[dc], s1); }
;                 if (NA) { const LAS float* br = rpb + ((hp * 2 + hh) * 15 + brow0 + 2 * ks + g) * 32;
; #pragma unroll
;                     for (int e = 0; e < 4; ++e) { s0[e] += br[bidx[e]]; s1[e] += br[bidx[4 + e]]; } }
;                 sc[gi][0] = s0; sc[gi][1] = s1;
;             }
;             SCHED_FENCE();
;             if (ks < NSTEP - 1) A2_WRITEK(nxt); else A2_WRITEV(nxt);
;             __syncthreads(); cb ^= 1;
.LBB0_229:
	s_lshl_b32 s74, s10, 19
	v_lshl_add_u64 v[136:137], v[116:117], 0, s[74:75]
	s_lshl_b32 s74, s10, 9
	v_lshl_add_u64 v[16:17], v[118:119], 0, s[74:75]
	v_add_co_u32_e32 v18, vcc, 0x4000, v16
	s_xor_b64 s[6:7], s[8:9], -1
	s_nop 0
	v_addc_co_u32_e32 v19, vcc, 0, v17, vcc
	global_load_dwordx4 v[48:51], v[16:17], off
	global_load_dwordx4 v[52:55], v[18:19], off
	v_add_co_u32_e32 v18, vcc, 0x8000, v16
	s_nop 1
	v_addc_co_u32_e32 v19, vcc, 0, v17, vcc
	v_add_co_u32_e32 v20, vcc, 0xc000, v16
	s_nop 1
	v_addc_co_u32_e32 v21, vcc, 0, v17, vcc
	global_load_dwordx4 v[56:59], v[18:19], off
	global_load_dwordx4 v[60:63], v[20:21], off
	v_add_co_u32_e32 v18, vcc, 0x10000, v16
	s_nop 1
	v_addc_co_u32_e32 v19, vcc, 0, v17, vcc
	v_add_co_u32_e32 v20, vcc, 0x14000, v16
	s_nop 1
	v_addc_co_u32_e32 v21, vcc, 0, v17, vcc
	global_load_dwordx4 v[64:67], v[18:19], off
	global_load_dwordx4 v[68:71], v[20:21], off
	v_add_co_u32_e32 v18, vcc, 0x18000, v16
	s_nop 1
	v_addc_co_u32_e32 v19, vcc, 0, v17, vcc
	v_add_co_u32_e32 v16, vcc, 0x1c000, v16
	s_nop 1
	v_addc_co_u32_e32 v17, vcc, 0, v17, vcc
	global_load_dwordx4 v[72:75], v[18:19], off
	global_load_dwordx4 v[76:79], v[16:17], off
	v_add_u32_e32 v84, v155, v158
	ds_read_b128 v[16:19], v84
	ds_read_b128 v[24:27], v84 offset:64
	ds_read_b128 v[20:23], v84 offset:4352
	s_waitcnt lgkmcnt(2)
	v_mfma_f32_16x16x32_bf16 v[16:19], v[16:19], v[4:7], 0
	ds_read_b128 v[32:35], v84 offset:8768
	ds_read_b128 v[40:43], v84 offset:17472
	ds_read_b128 v[28:31], v84 offset:13056
	s_waitcnt lgkmcnt(4)
	v_mfma_f32_16x16x32_bf16 v[16:19], v[24:27], v[0:3], v[16:19]
	ds_read_b128 v[24:27], v84 offset:4416
	ds_read_b128 v[36:39], v84 offset:21760
	ds_read_b128 v[80:83], v84 offset:26176
	s_waitcnt lgkmcnt(6)
	v_mfma_f32_16x16x32_bf16 v[20:23], v[20:23], v[4:7], 0
	ds_read_b128 v[44:47], v84 offset:30464
	s_waitcnt lgkmcnt(3)
	v_mfma_f32_16x16x32_bf16 v[20:23], v[24:27], v[0:3], v[20:23]
	ds_read_b128 v[240:243], v84 offset:128
	ds_read_b128 v[244:247], v84 offset:4480
	s_waitcnt lgkmcnt(1)
	v_mfma_f32_16x16x32_bf16 v[16:19], v[240:243], v[8:11], v[16:19]
	ds_read_b128 v[240:243], v84 offset:192
	s_waitcnt lgkmcnt(1)
	v_mfma_f32_16x16x32_bf16 v[20:23], v[244:247], v[8:11], v[20:23]
	ds_read_b128 v[244:247], v84 offset:4544
	s_waitcnt lgkmcnt(1)
	v_mfma_f32_16x16x32_bf16 v[16:19], v[240:243], v[12:15], v[16:19]
	ds_read_b128 v[240:243], v84 offset:8704
	s_waitcnt lgkmcnt(1)
	v_mfma_f32_16x16x32_bf16 v[20:23], v[244:247], v[12:15], v[20:23]
	s_waitcnt lgkmcnt(0)
	v_mfma_f32_16x16x32_bf16 v[24:27], v[240:243], v[4:7], 0
	v_mfma_f32_16x16x32_bf16 v[24:27], v[32:35], v[0:3], v[24:27]
	ds_read_b128 v[32:35], v84 offset:13120
	v_mfma_f32_16x16x32_bf16 v[28:31], v[28:31], v[4:7], 0
	s_waitcnt lgkmcnt(0)
	v_mfma_f32_16x16x32_bf16 v[28:31], v[32:35], v[0:3], v[28:31]
	ds_read_b128 v[240:243], v84 offset:8832
	ds_read_b128 v[244:247], v84 offset:13184
	s_waitcnt lgkmcnt(1)
	v_mfma_f32_16x16x32_bf16 v[24:27], v[240:243], v[8:11], v[24:27]
	ds_read_b128 v[240:243], v84 offset:8896
	s_waitcnt lgkmcnt(1)
	v_mfma_f32_16x16x32_bf16 v[28:31], v[244:247], v[8:11], v[28:31]
	ds_read_b128 v[244:247], v84 offset:13248
	s_waitcnt lgkmcnt(1)
	v_mfma_f32_16x16x32_bf16 v[24:27], v[240:243], v[12:15], v[24:27]
	ds_read_b128 v[240:243], v84 offset:17408
	s_waitcnt lgkmcnt(1)
	v_mfma_f32_16x16x32_bf16 v[28:31], v[244:247], v[12:15], v[28:31]
	s_waitcnt lgkmcnt(0)
	v_mfma_f32_16x16x32_bf16 v[32:35], v[240:243], v[4:7], 0
	v_mfma_f32_16x16x32_bf16 v[32:35], v[40:43], v[0:3], v[32:35]
	ds_read_b128 v[40:43], v84 offset:21824
	v_mfma_f32_16x16x32_bf16 v[36:39], v[36:39], v[4:7], 0
	s_waitcnt lgkmcnt(0)
	v_mfma_f32_16x16x32_bf16 v[36:39], v[40:43], v[0:3], v[36:39]
	ds_read_b128 v[240:243], v84 offset:17536
	ds_read_b128 v[244:247], v84 offset:21888
	s_waitcnt lgkmcnt(1)
	v_mfma_f32_16x16x32_bf16 v[32:35], v[240:243], v[8:11], v[32:35]
	ds_read_b128 v[240:243], v84 offset:17600
	s_waitcnt lgkmcnt(1)
	v_mfma_f32_16x16x32_bf16 v[36:39], v[244:247], v[8:11], v[36:39]
	ds_read_b128 v[244:247], v84 offset:21952
	s_waitcnt lgkmcnt(1)
	v_mfma_f32_16x16x32_bf16 v[32:35], v[240:243], v[12:15], v[32:35]
	ds_read_b128 v[240:243], v84 offset:26112
	s_waitcnt lgkmcnt(1)
	v_mfma_f32_16x16x32_bf16 v[36:39], v[244:247], v[12:15], v[36:39]
	s_waitcnt lgkmcnt(0)
	v_mfma_f32_16x16x32_bf16 v[40:43], v[240:243], v[4:7], 0
	v_mfma_f32_16x16x32_bf16 v[40:43], v[80:83], v[0:3], v[40:43]
	ds_read_b128 v[80:83], v84 offset:30528
	v_mfma_f32_16x16x32_bf16 v[44:47], v[44:47], v[4:7], 0
	s_waitcnt lgkmcnt(0)
	v_mfma_f32_16x16x32_bf16 v[44:47], v[80:83], v[0:3], v[44:47]
	ds_read_b128 v[240:243], v84 offset:26240
	ds_read_b128 v[244:247], v84 offset:30592
	s_waitcnt lgkmcnt(1)
	v_mfma_f32_16x16x32_bf16 v[40:43], v[240:243], v[8:11], v[40:43]
	ds_read_b128 v[240:243], v84 offset:26304
	s_waitcnt lgkmcnt(1)
	v_mfma_f32_16x16x32_bf16 v[44:47], v[244:247], v[8:11], v[44:47]
	ds_read_b128 v[244:247], v84 offset:30656
	s_waitcnt lgkmcnt(1)
	v_mfma_f32_16x16x32_bf16 v[40:43], v[240:243], v[12:15], v[40:43]
	s_waitcnt lgkmcnt(0)
	v_mfma_f32_16x16x32_bf16 v[44:47], v[244:247], v[12:15], v[44:47]
	v_add_co_u32_e32 v138, vcc, s47, v136
	s_mov_b32 s11, 0x20000
	s_nop 0
	v_addc_co_u32_e32 v139, vcc, 0, v137, vcc
	v_add_co_u32_e32 v140, vcc, s11, v136
	s_waitcnt vmcnt(7)
	ds_write_b128 v160, v[48:51]
	s_waitcnt vmcnt(6)
	ds_write_b128 v160, v[52:55] offset:4352
	s_waitcnt vmcnt(5)
	ds_write_b128 v160, v[56:59] offset:8704
	s_waitcnt vmcnt(4)
	ds_write_b128 v160, v[60:63] offset:13056
	s_waitcnt vmcnt(3)
	ds_write_b128 v160, v[64:67] offset:17408
	s_waitcnt vmcnt(2)
	ds_write_b128 v160, v[68:71] offset:21760
	s_waitcnt vmcnt(1)
	ds_write_b128 v160, v[72:75] offset:26112
	s_waitcnt vmcnt(0)
	ds_write_b128 v160, v[76:79] offset:30464
	v_addc_co_u32_e32 v141, vcc, 0, v137, vcc
	v_add_co_u32_e32 v142, vcc, s3, v136
	s_waitcnt lgkmcnt(0)
	s_nop 0
	v_addc_co_u32_e32 v143, vcc, 0, v137, vcc
	v_add_co_u32_e32 v146, vcc, s21, v136
	s_barrier
; #define LAS __attribute__((address_space(3)))
; #define SCHED_FENCE() __builtin_amdgcn_sched_barrier(0)
; __device__ __forceinline__ f32x4 mfma16(bf16x8 a, bf16x8 b, f32x4 c) { return __builtin_amdgcn_mfma_f32_16x16x32_bf16(a, b, c, 0, 0, 0); }
; #define A2_LOADK(hp_, s_) do { const char* _g = (const char*)(kg0 + (size_t)(s_) * kstep + (hp_) * 256); _Pragma("unroll") for (int j = 0; j < 8; ++j) t8[j] = *(const u32x4*)(_g + (size_t)j * (16 * kld * 2) + kgo); } while (0)
; #define A2_LOADV(hp_, s_) do { const char* _g = (const char*)(vg0 + (size_t)(hp_) * 256 * vld + (size_t)(s_) * vstep); _Pragma("unroll") for (int j = 0; j < 8; ++j) t8[j] = *(const u32x4*)(_g + (size_t)j * (32 * vld * 2) + vgo); } while (0)
; #define A2_WRITEK(buf_) do { _Pragma("unroll") for (int j = 0; j < 8; ++j) *(LAS u32x4*)((buf_) + klo + j * (16 * 272)) = t8[j]; } while (0)
; template <bool NA> ...
;     ...
;         for (int ks = 0; ks < NSTEP; ++ks) {
;             LAS unsigned char* cur = lds + cb * ABUF2; LAS unsigned char* nxt = lds + (cb ^ 1) * ABUF2;
;             if (ks < NSTEP - 1) A2_LOADK(hp, ks + 1); else A2_LOADV(hp, 0);
;             SCHED_FENCE();
; #pragma unroll
;             for (int g = 0; g < NGRP; ++g) {
;                 const int gi = ks * NGRP + g, koff = NA ? g * 64 + w0 : g * 32;
;                 const LAS unsigned char* kp = cur + (hh * 128 + koff + fr) * 272 + fq * 16;
;                 bf16x8 kf[2][4];
; #pragma unroll
;                 for (int a = 0; a < 2; ++a)
; #pragma unroll
;                     for (int dc = 0; dc < 4; ++dc) kf[a][dc] = *(const LAS bf16x8*)(kp + a * 16 * 272 + dc * 64);
;                 f32x4 s0 = (f32x4){0.f, 0.f, 0.f, 0.f}, s1 = (f32x4){0.f, 0.f, 0.f, 0.f};
; #pragma unroll
;                 for (int dc = 0; dc < 4; ++dc) { s0 = mfma16(kf[0][dc], qf[dc], s0); s1 = mfma16(kf[1][dc], qf[dc], s1); }
;                 if (NA) { const LAS float* br = rpb + ((hp * 2 + hh) * 15 + brow0 + 2 * ks + g) * 32;
; #pragma unroll
;                     for (int e = 0; e < 4; ++e) { s0[e] += br[bidx[e]]; s1[e] += br[bidx[4 + e]]; } }
;                 sc[gi][0] = s0; sc[gi][1] = s1;
;             }
;             SCHED_FENCE();
;             if (ks < NSTEP - 1) A2_WRITEK(nxt); else A2_WRITEV(nxt);
;             __syncthreads(); cb ^= 1;
	s_nop 0
	v_addc_co_u32_e32 v147, vcc, 0, v137, vcc
	v_add_co_u32_e32 v148, vcc, s20, v136
	s_nop 1
	v_addc_co_u32_e32 v149, vcc, 0, v137, vcc
	v_add_co_u32_e32 v150, vcc, s26, v136
	global_load_dwordx4 v[100:103], v[136:137], off
	global_load_dwordx4 v[104:107], v[138:139], off
	v_addc_co_u32_e32 v151, vcc, 0, v137, vcc
	v_add_co_u32_e32 v152, vcc, s48, v136
	global_load_dwordx4 v[108:111], v[140:141], off
	global_load_dwordx4 v[64:67], v[142:143], off
	global_load_dwordx4 v[72:75], v[146:147], off
	global_load_dwordx4 v[84:87], v[148:149], off
	v_addc_co_u32_e32 v153, vcc, 0, v137, vcc
	global_load_dwordx4 v[96:99], v[150:151], off
	global_load_dwordx4 v[92:95], v[152:153], off
	v_add_u32_e32 v233, v159, v158
	ds_read_b128 v[48:51], v233
	ds_read_b128 v[56:59], v233 offset:64
	ds_read_b128 v[52:55], v233 offset:4352
	s_waitcnt lgkmcnt(2)
	v_mfma_f32_16x16x32_bf16 v[48:51], v[48:51], v[4:7], 0
	ds_read_b128 v[68:71], v233 offset:8768
	ds_read_b128 v[76:79], v233 offset:21760
	ds_read_b128 v[80:83], v233 offset:17472
	s_waitcnt lgkmcnt(4)
	v_mfma_f32_16x16x32_bf16 v[48:51], v[56:59], v[0:3], v[48:51]
	ds_read_b128 v[56:59], v233 offset:4416
	ds_read_b128 v[234:237], v233 offset:26176
	ds_read_b128 v[88:91], v233 offset:30464
	s_waitcnt lgkmcnt(6)
	v_mfma_f32_16x16x32_bf16 v[52:55], v[52:55], v[4:7], 0
	s_waitcnt lgkmcnt(2)
	v_mfma_f32_16x16x32_bf16 v[52:55], v[56:59], v[0:3], v[52:55]
	ds_read_b128 v[240:243], v233 offset:128
	ds_read_b128 v[244:247], v233 offset:4480
	s_waitcnt lgkmcnt(1)
	v_mfma_f32_16x16x32_bf16 v[48:51], v[240:243], v[8:11], v[48:51]
	ds_read_b128 v[240:243], v233 offset:192
	s_waitcnt lgkmcnt(1)
	v_mfma_f32_16x16x32_bf16 v[52:55], v[244:247], v[8:11], v[52:55]
	ds_read_b128 v[244:247], v233 offset:4544
	s_waitcnt lgkmcnt(1)
	v_mfma_f32_16x16x32_bf16 v[56:59], v[240:243], v[12:15], v[48:51]
	s_waitcnt lgkmcnt(0)
	v_mfma_f32_16x16x32_bf16 v[60:63], v[244:247], v[12:15], v[52:55]
	ds_read_b128 v[48:51], v233 offset:8704
	s_nop 1
	ds_read_b128 v[52:55], v233 offset:13056
	s_waitcnt lgkmcnt(1)
	v_mfma_f32_16x16x32_bf16 v[48:51], v[48:51], v[4:7], 0
	v_mfma_f32_16x16x32_bf16 v[48:51], v[68:71], v[0:3], v[48:51]
	ds_read_b128 v[68:71], v233 offset:13120
	s_waitcnt lgkmcnt(1)
	v_mfma_f32_16x16x32_bf16 v[52:55], v[52:55], v[4:7], 0
	s_waitcnt lgkmcnt(0)
	v_mfma_f32_16x16x32_bf16 v[52:55], v[68:71], v[0:3], v[52:55]
	ds_read_b128 v[240:243], v233 offset:8832
	ds_read_b128 v[244:247], v233 offset:13184
	s_waitcnt lgkmcnt(1)
	v_mfma_f32_16x16x32_bf16 v[48:51], v[240:243], v[8:11], v[48:51]
	ds_read_b128 v[240:243], v233 offset:8896
	s_waitcnt lgkmcnt(1)
	v_mfma_f32_16x16x32_bf16 v[52:55], v[244:247], v[8:11], v[52:55]
	ds_read_b128 v[244:247], v233 offset:13248
	s_waitcnt lgkmcnt(1)
	v_mfma_f32_16x16x32_bf16 v[48:51], v[240:243], v[12:15], v[48:51]
	ds_read_b128 v[240:243], v233 offset:17408
	s_waitcnt lgkmcnt(1)
	v_mfma_f32_16x16x32_bf16 v[52:55], v[244:247], v[12:15], v[52:55]
	s_waitcnt lgkmcnt(0)
	v_mfma_f32_16x16x32_bf16 v[68:71], v[240:243], v[4:7], 0
	v_mfma_f32_16x16x32_bf16 v[68:71], v[80:83], v[0:3], v[68:71]
	ds_read_b128 v[80:83], v233 offset:21824
	v_mfma_f32_16x16x32_bf16 v[76:79], v[76:79], v[4:7], 0
	s_waitcnt lgkmcnt(0)
	v_mfma_f32_16x16x32_bf16 v[76:79], v[80:83], v[0:3], v[76:79]
	ds_read_b128 v[240:243], v233 offset:17536
	ds_read_b128 v[244:247], v233 offset:21888
	s_waitcnt lgkmcnt(1)
	v_mfma_f32_16x16x32_bf16 v[68:71], v[240:243], v[8:11], v[68:71]
	ds_read_b128 v[240:243], v233 offset:17600
	s_waitcnt lgkmcnt(1)
	v_mfma_f32_16x16x32_bf16 v[76:79], v[244:247], v[8:11], v[76:79]
	ds_read_b128 v[244:247], v233 offset:21952
	s_waitcnt lgkmcnt(1)
	v_mfma_f32_16x16x32_bf16 v[68:71], v[240:243], v[12:15], v[68:71]
	ds_read_b128 v[240:243], v233 offset:26112
	s_waitcnt lgkmcnt(1)
	v_mfma_f32_16x16x32_bf16 v[76:79], v[244:247], v[12:15], v[76:79]
	s_waitcnt lgkmcnt(0)
	v_mfma_f32_16x16x32_bf16 v[80:83], v[240:243], v[4:7], 0
	v_mfma_f32_16x16x32_bf16 v[80:83], v[234:237], v[0:3], v[80:83]
	ds_read_b128 v[234:237], v233 offset:30528
	v_mfma_f32_16x16x32_bf16 v[88:91], v[88:91], v[4:7], 0
	s_waitcnt lgkmcnt(0)
	v_mfma_f32_16x16x32_bf16 v[88:91], v[234:237], v[0:3], v[88:91]
	ds_read_b128 v[240:243], v233 offset:26240
	ds_read_b128 v[244:247], v233 offset:30592
	s_waitcnt lgkmcnt(1)
	v_mfma_f32_16x16x32_bf16 v[80:83], v[240:243], v[8:11], v[80:83]
	ds_read_b128 v[240:243], v233 offset:26304
	s_waitcnt lgkmcnt(1)
	v_mfma_f32_16x16x32_bf16 v[88:91], v[244:247], v[8:11], v[88:91]
	s_waitcnt lgkmcnt(0)
	v_mfma_f32_16x16x32_bf16 v[80:83], v[240:243], v[12:15], v[80:83]
	ds_read_b128 v[234:237], v233 offset:30656
	s_waitcnt lgkmcnt(0)
	v_mfma_f32_16x16x32_bf16 v[88:91], v[234:237], v[12:15], v[88:91]
	s_waitcnt vmcnt(7)
	ds_write_b128 v161, v[100:103]
	s_waitcnt vmcnt(6)
	ds_write_b128 v161, v[104:107] offset:8704
	s_waitcnt vmcnt(5)
; __device__ __forceinline__ unsigned pk2(float lo, float hi) { unsigned r; asm("v_cvt_pk_bf16_f32 %0, %1, %2" : "=v"(r) : "v"(lo), "v"(hi)); return r; }
; __device__ __forceinline__ float shfl_xor_l(float v, int lane, int mask) { return __int_as_float(__builtin_amdgcn_ds_bpermute((lane ^ mask) << 2, __float_as_int(v))); }
; __device__ __forceinline__ float fexp2(float x) { return __builtin_amdgcn_exp2f(x); }
; #define A2_WRITEK(buf_) do { _Pragma("unroll") for (int j = 0; j < 8; ++j) *(LAS u32x4*)((buf_) + klo + j * (16 * 272)) = t8[j]; } while (0)
; #define A2_WRITEV(buf_) do { _Pragma("unroll") for (int j = 0; j < 8; ++j) *(LAS u32x4*)((buf_) + vlo + j * (32 * 272)) = t8[j]; } while (0)
; template <bool NA> ...
;     ...
;             if (ks < NSTEP - 1) A2_WRITEK(nxt); else A2_WRITEV(nxt);
;             __syncthreads(); cb ^= 1;
;         }
;         float mx = -3.0e38f;
; #pragma unroll
;         for (int gi = 0; gi < 8; ++gi)
; #pragma unroll
;             for (int a = 0; a < 2; ++a) mx = fmaxf(mx, fmaxf(fmaxf(sc[gi][a].x, sc[gi][a].y), fmaxf(sc[gi][a].z, sc[gi][a].w)));
;         mx = fmaxf(mx, shfl_xor_l(mx, lane, 16)); mx = fmaxf(mx, shfl_xor_l(mx, lane, 32));
;         float l = 0.f; bf16x8 pb[8];
; #pragma unroll
;         for (int gi = 0; gi < 8; ++gi) {
;             f32x4 p0 = sc[gi][0], p1 = sc[gi][1];
; #pragma unroll
;             for (int e = 0; e < 4; ++e) { p0[e] = fexp2(p0[e] - mx); p1[e] = fexp2(p1[e] - mx); }
;             l += ((p0.x + p0.y) + (p0.z + p0.w)) + ((p1.x + p1.y) + (p1.z + p1.w));
;             u32x4 pw; pw.x = pk2(p0.x, p0.y); pw.y = pk2(p0.z, p0.w); pw.z = pk2(p1.x, p1.y); pw.w = pk2(p1.z, p1.w);
;             pb[gi] = __builtin_bit_cast(bf16x8, pw);
;         }
	ds_write_b128 v161, v[108:111] offset:17408
	v_max_f32_e32 v100, v19, v19
	v_max_f32_e32 v101, v18, v18
	v_max_f32_e32 v100, v101, v100
	v_max_f32_e32 v101, v23, v23
	v_max_f32_e32 v102, v22, v22
	v_max_f32_e32 v101, v102, v101
	v_max3_f32 v100, v16, v17, v100
	v_max3_f32 v101, v20, v21, v101
	v_max3_f32 v100, v100, s27, v101
	v_max_f32_e32 v101, v27, v27
	v_max_f32_e32 v102, v26, v26
	v_max_f32_e32 v101, v102, v101
	v_max_f32_e32 v102, v31, v31
	v_max_f32_e32 v103, v30, v30
	v_max_f32_e32 v102, v103, v102
	v_max3_f32 v101, v24, v25, v101
	v_max3_f32 v102, v28, v29, v102
	v_max3_f32 v100, v100, v101, v102
	v_max_f32_e32 v101, v35, v35
	v_max_f32_e32 v102, v34, v34
	v_max_f32_e32 v101, v102, v101
	v_max_f32_e32 v102, v39, v39
	v_max_f32_e32 v103, v38, v38
	v_max_f32_e32 v102, v103, v102
	v_max3_f32 v101, v32, v33, v101
	v_max3_f32 v102, v36, v37, v102
	v_max3_f32 v100, v100, v101, v102
	v_max_f32_e32 v101, v43, v43
	v_max_f32_e32 v102, v42, v42
	v_max_f32_e32 v101, v102, v101
	v_max_f32_e32 v102, v47, v47
	v_max_f32_e32 v103, v46, v46
	v_max_f32_e32 v102, v103, v102
	v_max3_f32 v101, v40, v41, v101
	v_max3_f32 v102, v44, v45, v102
	v_max3_f32 v100, v100, v101, v102
	v_max_f32_e32 v101, v59, v59
	v_max_f32_e32 v102, v58, v58
	v_max_f32_e32 v101, v102, v101
	v_max_f32_e32 v102, v63, v63
	v_max_f32_e32 v103, v62, v62
	v_max_f32_e32 v102, v103, v102
	v_max3_f32 v101, v56, v57, v101
	v_max3_f32 v102, v60, v61, v102
	v_max3_f32 v100, v100, v101, v102
	v_max_f32_e32 v101, v51, v51
	v_max_f32_e32 v102, v50, v50
	v_max_f32_e32 v101, v102, v101
	v_max_f32_e32 v102, v55, v55
	v_max_f32_e32 v103, v54, v54
	v_max_f32_e32 v102, v103, v102
	v_max3_f32 v101, v48, v49, v101
	v_max3_f32 v102, v52, v53, v102
	v_max3_f32 v100, v100, v101, v102
	v_max_f32_e32 v101, v71, v71
	v_max_f32_e32 v102, v70, v70
	v_max_f32_e32 v101, v102, v101
	v_max_f32_e32 v102, v79, v79
	v_max_f32_e32 v103, v78, v78
	v_max_f32_e32 v102, v103, v102
	v_max3_f32 v101, v68, v69, v101
	v_max3_f32 v102, v76, v77, v102
	v_max3_f32 v100, v100, v101, v102
	v_max_f32_e32 v101, v83, v83
	v_max_f32_e32 v102, v82, v82
	v_max_f32_e32 v101, v102, v101
	v_max_f32_e32 v102, v91, v91
	v_max_f32_e32 v103, v90, v90
	v_max_f32_e32 v102, v103, v102
	v_max3_f32 v101, v80, v81, v101
	v_max3_f32 v102, v88, v89, v102
	v_max3_f32 v100, v100, v101, v102
	ds_bpermute_b32 v101, v156, v100
	s_waitcnt vmcnt(4)
	ds_write_b128 v161, v[64:67] offset:26112
	s_waitcnt vmcnt(3)
	ds_write_b128 v161, v[72:75] offset:34816
	s_waitcnt vmcnt(2)
	ds_write_b128 v161, v[84:87] offset:43520
	s_waitcnt vmcnt(1)
	ds_write_b128 v161, v[96:99] offset:52224
	s_waitcnt vmcnt(0)
	ds_write_b128 v161, v[92:95] offset:60928
	s_waitcnt lgkmcnt(0)
	s_barrier
	v_max_f32_e32 v64, v101, v101
	v_max_f32_e32 v64, v100, v64
	ds_bpermute_b32 v65, v157, v64
	s_waitcnt lgkmcnt(0)
	v_max_f32_e32 v65, v65, v65
	v_max_f32_e32 v96, v64, v65
	v_sub_f32_e32 v16, v16, v96
	v_sub_f32_e32 v17, v17, v96
	v_sub_f32_e32 v18, v18, v96
	v_sub_f32_e32 v19, v19, v96
	v_exp_f32_e32 v16, v16
	v_sub_f32_e32 v20, v20, v96
	v_exp_f32_e32 v17, v17
	v_sub_f32_e32 v21, v21, v96
	v_exp_f32_e32 v18, v18
	v_sub_f32_e32 v22, v22, v96
	v_exp_f32_e32 v19, v19
	v_sub_f32_e32 v23, v23, v96
	v_exp_f32_e32 v20, v20
	v_exp_f32_e32 v21, v21
	v_exp_f32_e32 v22, v22
	v_exp_f32_e32 v23, v23
	v_add_f32_e32 v64, v16, v17
	v_add_f32_e32 v65, v18, v19
	v_add_f32_e32 v64, v64, v65
	v_add_f32_e32 v65, v20, v21
	v_add_f32_e32 v66, v22, v23
	v_cvt_pk_bf16_f32 v92, v16, v17
	v_cvt_pk_bf16_f32 v93, v18, v19
	v_cvt_pk_bf16_f32 v94, v20, v21
	v_cvt_pk_bf16_f32 v95, v22, v23
	v_sub_f32_e32 v16, v24, v96
	v_sub_f32_e32 v18, v25, v96
	v_sub_f32_e32 v20, v26, v96
	v_sub_f32_e32 v22, v27, v96
	v_exp_f32_e32 v16, v16
	v_sub_f32_e32 v17, v28, v96
	v_exp_f32_e32 v18, v18
	v_sub_f32_e32 v19, v29, v96
	v_exp_f32_e32 v20, v20
	v_sub_f32_e32 v21, v30, v96
	v_exp_f32_e32 v22, v22
	v_sub_f32_e32 v23, v31, v96
	v_exp_f32_e32 v17, v17
	v_exp_f32_e32 v19, v19
	v_exp_f32_e32 v21, v21
	v_exp_f32_e32 v23, v23
	v_add_f32_e32 v24, v16, v18
	v_add_f32_e32 v25, v20, v22
	v_cvt_pk_bf16_f32 v84, v16, v18
	v_cvt_pk_bf16_f32 v85, v20, v22
	v_sub_f32_e32 v16, v32, v96
	v_sub_f32_e32 v18, v33, v96
	v_sub_f32_e32 v20, v34, v96
	v_sub_f32_e32 v22, v35, v96
	v_add_f32_e32 v24, v24, v25
	v_add_f32_e32 v25, v17, v19
	v_add_f32_e32 v26, v21, v23
	v_cvt_pk_bf16_f32 v86, v17, v19
	v_cvt_pk_bf16_f32 v87, v21, v23
	v_exp_f32_e32 v16, v16
	v_sub_f32_e32 v17, v36, v96
	v_exp_f32_e32 v18, v18
	v_sub_f32_e32 v19, v37, v96
	v_exp_f32_e32 v20, v20
	v_sub_f32_e32 v21, v38, v96
	v_exp_f32_e32 v22, v22
	v_sub_f32_e32 v23, v39, v96
	v_exp_f32_e32 v17, v17
	v_exp_f32_e32 v19, v19
	v_exp_f32_e32 v21, v21
	v_exp_f32_e32 v23, v23
	v_add_f32_e32 v25, v25, v26
	v_add_f32_e32 v24, v24, v25
	v_add_f32_e32 v25, v16, v18
	v_add_f32_e32 v26, v20, v22
	v_cvt_pk_bf16_f32 v72, v16, v18
	v_cvt_pk_bf16_f32 v73, v20, v22
	v_sub_f32_e32 v16, v40, v96
	v_sub_f32_e32 v18, v41, v96
	v_sub_f32_e32 v20, v42, v96
	v_sub_f32_e32 v22, v43, v96
	v_add_f32_e32 v65, v65, v66
	v_add_f32_e32 v25, v25, v26
	v_add_f32_e32 v26, v17, v19
	v_add_f32_e32 v27, v21, v23
	v_cvt_pk_bf16_f32 v74, v17, v19
	v_cvt_pk_bf16_f32 v75, v21, v23
	v_exp_f32_e32 v16, v16
	v_sub_f32_e32 v17, v44, v96
	v_exp_f32_e32 v18, v18
	v_sub_f32_e32 v19, v45, v96
	v_exp_f32_e32 v20, v20
	v_sub_f32_e32 v21, v46, v96
	v_exp_f32_e32 v22, v22
	v_sub_f32_e32 v23, v47, v96
	v_add_f32_e32 v64, v64, v65
	v_exp_f32_e32 v17, v17
	v_exp_f32_e32 v19, v19
	v_exp_f32_e32 v21, v21
	v_exp_f32_e32 v23, v23
	v_add_f32_e32 v64, 0, v64
	v_add_f32_e32 v26, v26, v27
	v_add_f32_e32 v24, v24, v64
	v_add_f32_e32 v25, v25, v26
; #define LAS __attribute__((address_space(3)))
; #define SCHED_FENCE() __builtin_amdgcn_sched_barrier(0)
; __device__ __forceinline__ unsigned pk2(float lo, float hi) { unsigned r; asm("v_cvt_pk_bf16_f32 %0, %1, %2" : "=v"(r) : "v"(lo), "v"(hi)); return r; }
; __device__ __forceinline__ float shfl_xor_l(float v, int lane, int mask) { return __int_as_float(__builtin_amdgcn_ds_bpermute((lane ^ mask) << 2, __float_as_int(v))); }
; __device__ __forceinline__ float fexp2(float x) { return __builtin_amdgcn_exp2f(x); }
; template <bool NA> ...
;     ...
; #pragma unroll
;         for (int gi = 0; gi < 8; ++gi) {
;             f32x4 p0 = sc[gi][0], p1 = sc[gi][1];
; #pragma unroll
;             for (int e = 0; e < 4; ++e) { p0[e] = fexp2(p0[e] - mx); p1[e] = fexp2(p1[e] - mx); }
;             l += ((p0.x + p0.y) + (p0.z + p0.w)) + ((p1.x + p1.y) + (p1.z + p1.w));
;             u32x4 pw; pw.x = pk2(p0.x, p0.y); pw.y = pk2(p0.z, p0.w); pw.z = pk2(p1.x, p1.y); pw.w = pk2(p1.z, p1.w);
;             pb[gi] = __builtin_bit_cast(bf16x8, pw);
;         }
;         l += shfl_xor_l(l, lane, 16); l += shfl_xor_l(l, lane, 32);
;         f32x4 o[8];
; #pragma unroll
;         for (int d = 0; d < 8; ++d) o[d] = (f32x4){0.f, 0.f, 0.f, 0.f};
; #pragma unroll
;         for (int vs = 0; vs < NSTEP; ++vs) {
;             LAS unsigned char* cur = lds + cb * ABUF2; LAS unsigned char* nxt = lds + (cb ^ 1) * ABUF2;
;             if (vs == NSTEP - 1 && hp < NHP - 1) {
;                 const bf16_t* qa = qbase + ((hp + 1) * 2 + hh) * 128;
; #pragma unroll
;                 for (int dc = 0; dc < 4; ++dc) qfn[dc] = *(const bf16x8*)(qa + dc * 32);
;             }
;             if (vs < NSTEP - 1) A2_LOADV(hp, vs + 1); else if (hp < NHP - 1) A2_LOADK(hp + 1, 0);
;             SCHED_FENCE();
; #pragma unroll
;             for (int g = 0; g < NGRP; ++g) {
;                 const int gi = vs * NGRP + g, voff = NA ? g * 64 + w0 : g * 32;
;                 const LAS unsigned char* vp = cur + (hh * 128 + fr) * 272 + (voff + fq * 4) * 2;
; #pragma unroll
;                 for (int d = 0; d < 8; ++d) {
;                     const u32x2 lo = *(const LAS u32x2*)(vp + d * 16 * 272), hi = *(const LAS u32x2*)(vp + d * 16 * 272 + 32);
;                     u32x4 vw; vw.x = lo.x; vw.y = lo.y; vw.z = hi.x; vw.w = hi.y;
;                     o[d] = mfma16(__builtin_bit_cast(bf16x8, vw), pb[gi], o[d]);
	v_add_f32_e32 v24, v25, v24
	v_add_f32_e32 v25, v16, v18
	v_add_f32_e32 v26, v20, v22
	v_cvt_pk_bf16_f32 v64, v16, v18
	v_cvt_pk_bf16_f32 v65, v20, v22
	v_sub_f32_e32 v16, v56, v96
	v_sub_f32_e32 v18, v57, v96
	v_sub_f32_e32 v20, v58, v96
	v_sub_f32_e32 v22, v59, v96
	v_add_f32_e32 v25, v25, v26
	v_add_f32_e32 v26, v17, v19
	v_add_f32_e32 v27, v21, v23
	v_cvt_pk_bf16_f32 v66, v17, v19
	v_cvt_pk_bf16_f32 v67, v21, v23
	v_exp_f32_e32 v16, v16
	v_sub_f32_e32 v17, v60, v96
	v_exp_f32_e32 v18, v18
	v_sub_f32_e32 v19, v61, v96
	v_exp_f32_e32 v20, v20
	v_sub_f32_e32 v21, v62, v96
	v_exp_f32_e32 v22, v22
	v_sub_f32_e32 v23, v63, v96
	v_exp_f32_e32 v17, v17
	v_exp_f32_e32 v19, v19
	v_exp_f32_e32 v21, v21
	v_exp_f32_e32 v23, v23
	v_add_f32_e32 v26, v26, v27
	v_add_f32_e32 v25, v25, v26
	v_add_f32_e32 v24, v25, v24
	v_add_f32_e32 v25, v16, v18
	v_add_f32_e32 v26, v20, v22
	v_cvt_pk_bf16_f32 v56, v16, v18
	v_sub_f32_e32 v16, v48, v96
	v_add_f32_e32 v25, v25, v26
	v_add_f32_e32 v26, v17, v19
	v_add_f32_e32 v27, v21, v23
	v_exp_f32_e32 v48, v16
	v_sub_f32_e32 v16, v52, v96
	v_add_f32_e32 v26, v26, v27
	v_exp_f32_e32 v52, v16
	v_sub_f32_e32 v16, v49, v96
	v_add_f32_e32 v25, v25, v26
	v_exp_f32_e32 v49, v16
	v_sub_f32_e32 v16, v53, v96
	v_add_f32_e32 v60, v25, v24
	v_cvt_pk_bf16_f32 v57, v20, v22
	v_cvt_pk_bf16_f32 v58, v17, v19
	v_cvt_pk_bf16_f32 v59, v21, v23
	v_exp_f32_e32 v53, v16
	global_load_dwordx4 v[44:47], v[136:137], off offset:256
	global_load_dwordx4 v[40:43], v[138:139], off offset:256
	global_load_dwordx4 v[36:39], v[140:141], off offset:256
	global_load_dwordx4 v[32:35], v[142:143], off offset:256
	global_load_dwordx4 v[28:31], v[146:147], off offset:256
	global_load_dwordx4 v[24:27], v[148:149], off offset:256
	global_load_dwordx4 v[16:19], v[150:151], off offset:256
	global_load_dwordx4 v[20:23], v[152:153], off offset:256
	v_sub_f32_e32 v50, v50, v96
	v_sub_f32_e32 v51, v51, v96
	v_exp_f32_e32 v50, v50
	v_sub_f32_e32 v54, v54, v96
	v_exp_f32_e32 v51, v51
	v_sub_f32_e32 v55, v55, v96
	v_exp_f32_e32 v54, v54
	v_exp_f32_e32 v55, v55
	v_add_f32_e32 v61, v48, v49
	v_add_f32_e32 v62, v50, v51
	v_add_f32_e32 v61, v61, v62
	v_add_f32_e32 v62, v52, v53
	v_add_f32_e32 v63, v54, v55
	v_add_f32_e32 v62, v62, v63
	v_add_f32_e32 v61, v61, v62
	v_cvt_pk_bf16_f32 v62, v52, v53
	v_sub_f32_e32 v52, v70, v96
	v_exp_f32_e32 v53, v52
	v_sub_f32_e32 v52, v78, v96
	v_add_f32_e32 v97, v61, v60
	v_cvt_pk_bf16_f32 v60, v48, v49
	v_cvt_pk_bf16_f32 v61, v50, v51
	v_cvt_pk_bf16_f32 v63, v54, v55
	v_sub_f32_e32 v48, v68, v96
	v_sub_f32_e32 v50, v69, v96
	v_exp_f32_e32 v55, v52
	v_sub_f32_e32 v52, v71, v96
	v_exp_f32_e32 v48, v48
	v_sub_f32_e32 v49, v76, v96
	v_exp_f32_e32 v50, v50
	v_sub_f32_e32 v51, v77, v96
	v_exp_f32_e32 v54, v52
	v_sub_f32_e32 v52, v79, v96
	v_exp_f32_e32 v49, v49
	v_exp_f32_e32 v51, v51
	v_exp_f32_e32 v68, v52
	v_add_f32_e32 v52, v48, v50
	v_add_f32_e32 v69, v53, v54
	v_add_f32_e32 v52, v52, v69
	v_add_f32_e32 v69, v49, v51
	v_add_f32_e32 v70, v55, v68
	v_add_f32_e32 v69, v69, v70
	v_add_f32_e32 v52, v52, v69
	v_sub_f32_e32 v69, v80, v96
	v_sub_f32_e32 v71, v81, v96
	v_sub_f32_e32 v77, v82, v96
	v_sub_f32_e32 v79, v83, v96
	v_exp_f32_e32 v69, v69
	v_sub_f32_e32 v70, v88, v96
	v_exp_f32_e32 v71, v71
	v_sub_f32_e32 v76, v89, v96
	v_exp_f32_e32 v77, v77
	v_sub_f32_e32 v78, v90, v96
	v_exp_f32_e32 v79, v79
	v_sub_f32_e32 v80, v91, v96
	v_exp_f32_e32 v70, v70
	v_exp_f32_e32 v76, v76
	v_exp_f32_e32 v78, v78
	v_exp_f32_e32 v80, v80
	v_add_f32_e32 v81, v69, v71
	v_add_f32_e32 v82, v77, v79
	v_add_f32_e32 v81, v81, v82
	v_add_f32_e32 v82, v70, v76
	v_add_f32_e32 v83, v78, v80
	v_add_f32_e32 v82, v82, v83
	v_add_f32_e32 v52, v52, v97
	v_add_f32_e32 v81, v81, v82
	v_add_f32_e32 v81, v81, v52
	ds_bpermute_b32 v82, v156, v81
	v_cvt_pk_bf16_f32 v52, v48, v50
	v_cvt_pk_bf16_f32 v53, v53, v54
	v_cvt_pk_bf16_f32 v54, v49, v51
	v_cvt_pk_bf16_f32 v55, v55, v68
	s_waitcnt lgkmcnt(0)
	v_add_f32_e32 v96, v81, v82
	ds_bpermute_b32 v97, v157, v96
	v_cvt_pk_bf16_f32 v48, v69, v71
	v_cvt_pk_bf16_f32 v49, v77, v79
	v_cvt_pk_bf16_f32 v50, v70, v76
	v_cvt_pk_bf16_f32 v51, v78, v80
	v_add_u32_e32 v110, 0x1000, v144
	v_add_u32_e32 v111, 0x2000, v144
	v_add_u32_e32 v146, 0x3000, v144
	v_add_u32_e32 v147, 0x4000, v144
	v_add_u32_e32 v148, 0x5000, v144
	v_add_u32_e32 v149, 0x6000, v144
	v_add_u32_e32 v150, 0x7000, v144
	ds_read2_b64 v[68:71], v144 offset1:4
	ds_read2_b64 v[76:79], v110 offset0:32 offset1:36
	ds_read2_b64 v[80:83], v111 offset0:64 offset1:68
	ds_read2_b64 v[88:91], v146 offset0:96 offset1:100
	ds_read2_b64 v[98:101], v147 offset0:128 offset1:132
	ds_read2_b64 v[102:105], v148 offset0:160 offset1:164
	ds_read2_b64 v[106:109], v149 offset0:192 offset1:196
	ds_read2_b64 v[136:139], v150 offset0:224 offset1:228
	s_waitcnt lgkmcnt(7)
	v_mfma_f32_16x16x32_bf16 v[68:71], v[68:71], v[92:95], 0
	s_waitcnt lgkmcnt(6)
; #define LAS __attribute__((address_space(3)))
; #define SCHED_FENCE() __builtin_amdgcn_sched_barrier(0)
; __device__ __forceinline__ f32x4 mfma16(bf16x8 a, bf16x8 b, f32x4 c) { return __builtin_amdgcn_mfma_f32_16x16x32_bf16(a, b, c, 0, 0, 0); }
; #define A2_LOADK(hp_, s_) do { const char* _g = (const char*)(kg0 + (size_t)(s_) * kstep + (hp_) * 256); _Pragma("unroll") for (int j = 0; j < 8; ++j) t8[j] = *(const u32x4*)(_g + (size_t)j * (16 * kld * 2) + kgo); } while (0)
; #define A2_LOADV(hp_, s_) do { const char* _g = (const char*)(vg0 + (size_t)(hp_) * 256 * vld + (size_t)(s_) * vstep); _Pragma("unroll") for (int j = 0; j < 8; ++j) t8[j] = *(const u32x4*)(_g + (size_t)j * (32 * vld * 2) + vgo); } while (0)
; #define A2_WRITEK(buf_) do { _Pragma("unroll") for (int j = 0; j < 8; ++j) *(LAS u32x4*)((buf_) + klo + j * (16 * 272)) = t8[j]; } while (0)
; #define A2_WRITEV(buf_) do { _Pragma("unroll") for (int j = 0; j < 8; ++j) *(LAS u32x4*)((buf_) + vlo + j * (32 * 272)) = t8[j]; } while (0)
; template <bool NA> ...
;     ...
;         for (int vs = 0; vs < NSTEP; ++vs) {
;             LAS unsigned char* cur = lds + cb * ABUF2; LAS unsigned char* nxt = lds + (cb ^ 1) * ABUF2;
;             if (vs == NSTEP - 1 && hp < NHP - 1) {
;                 const bf16_t* qa = qbase + ((hp + 1) * 2 + hh) * 128;
; #pragma unroll
;                 for (int dc = 0; dc < 4; ++dc) qfn[dc] = *(const bf16x8*)(qa + dc * 32);
;             }
;             if (vs < NSTEP - 1) A2_LOADV(hp, vs + 1); else if (hp < NHP - 1) A2_LOADK(hp + 1, 0);
;             SCHED_FENCE();
; #pragma unroll
;             for (int g = 0; g < NGRP; ++g) {
;                 const int gi = vs * NGRP + g, voff = NA ? g * 64 + w0 : g * 32;
;                 const LAS unsigned char* vp = cur + (hh * 128 + fr) * 272 + (voff + fq * 4) * 2;
; #pragma unroll
;                 for (int d = 0; d < 8; ++d) {
;                     const u32x2 lo = *(const LAS u32x2*)(vp + d * 16 * 272), hi = *(const LAS u32x2*)(vp + d * 16 * 272 + 32);
;                     u32x4 vw; vw.x = lo.x; vw.y = lo.y; vw.z = hi.x; vw.w = hi.y;
;                     o[d] = mfma16(__builtin_bit_cast(bf16x8, vw), pb[gi], o[d]);
;                 }
;             }
;             SCHED_FENCE();
;             if (vs < NSTEP - 1) A2_WRITEV(nxt); else if (hp < NHP - 1) A2_WRITEK(nxt);
;             __syncthreads(); cb ^= 1;
	v_mfma_f32_16x16x32_bf16 v[76:79], v[76:79], v[92:95], 0
	s_waitcnt lgkmcnt(5)
	v_mfma_f32_16x16x32_bf16 v[80:83], v[80:83], v[92:95], 0
	s_waitcnt lgkmcnt(4)
	v_mfma_f32_16x16x32_bf16 v[88:91], v[88:91], v[92:95], 0
	s_waitcnt lgkmcnt(3)
	v_mfma_f32_16x16x32_bf16 v[98:101], v[98:101], v[92:95], 0
	s_waitcnt lgkmcnt(2)
	v_mfma_f32_16x16x32_bf16 v[102:105], v[102:105], v[92:95], 0
	s_waitcnt lgkmcnt(1)
	v_mfma_f32_16x16x32_bf16 v[106:109], v[106:109], v[92:95], 0
	s_waitcnt lgkmcnt(0)
	v_mfma_f32_16x16x32_bf16 v[92:95], v[136:139], v[92:95], 0
	ds_read2_b64 v[240:243], v144 offset0:8 offset1:12
	ds_read2_b64 v[244:247], v110 offset0:40 offset1:44
	s_waitcnt lgkmcnt(1)
	v_mfma_f32_16x16x32_bf16 v[68:71], v[240:243], v[84:87], v[68:71]
	ds_read2_b64 v[240:243], v111 offset0:72 offset1:76
	s_waitcnt lgkmcnt(1)
	v_mfma_f32_16x16x32_bf16 v[76:79], v[244:247], v[84:87], v[76:79]
	ds_read2_b64 v[244:247], v146 offset0:104 offset1:108
	s_waitcnt lgkmcnt(1)
	v_mfma_f32_16x16x32_bf16 v[80:83], v[240:243], v[84:87], v[80:83]
	ds_read2_b64 v[240:243], v147 offset0:136 offset1:140
	s_waitcnt lgkmcnt(1)
	v_mfma_f32_16x16x32_bf16 v[88:91], v[244:247], v[84:87], v[88:91]
	ds_read2_b64 v[244:247], v148 offset0:168 offset1:172
	s_waitcnt lgkmcnt(1)
	v_mfma_f32_16x16x32_bf16 v[98:101], v[240:243], v[84:87], v[98:101]
	ds_read2_b64 v[240:243], v149 offset0:200 offset1:204
	s_waitcnt lgkmcnt(1)
	v_mfma_f32_16x16x32_bf16 v[102:105], v[244:247], v[84:87], v[102:105]
	ds_read2_b64 v[244:247], v150 offset0:232 offset1:236
	s_waitcnt lgkmcnt(1)
	v_mfma_f32_16x16x32_bf16 v[106:109], v[240:243], v[84:87], v[106:109]
	ds_read2_b64 v[240:243], v144 offset0:16 offset1:20
	s_waitcnt lgkmcnt(1)
	v_mfma_f32_16x16x32_bf16 v[84:87], v[244:247], v[84:87], v[92:95]
	ds_read2_b64 v[244:247], v110 offset0:48 offset1:52
	s_waitcnt lgkmcnt(1)
	v_mfma_f32_16x16x32_bf16 v[68:71], v[240:243], v[72:75], v[68:71]
	ds_read2_b64 v[240:243], v111 offset0:80 offset1:84
	s_waitcnt lgkmcnt(1)
	v_mfma_f32_16x16x32_bf16 v[76:79], v[244:247], v[72:75], v[76:79]
	ds_read2_b64 v[244:247], v146 offset0:112 offset1:116
	s_waitcnt lgkmcnt(1)
	v_mfma_f32_16x16x32_bf16 v[80:83], v[240:243], v[72:75], v[80:83]
	ds_read2_b64 v[240:243], v147 offset0:144 offset1:148
	s_waitcnt lgkmcnt(1)
	v_mfma_f32_16x16x32_bf16 v[136:139], v[244:247], v[72:75], v[88:91]
	ds_read2_b64 v[244:247], v148 offset0:176 offset1:180
	s_waitcnt lgkmcnt(1)
	v_mfma_f32_16x16x32_bf16 v[98:101], v[240:243], v[72:75], v[98:101]
	ds_read2_b64 v[240:243], v149 offset0:208 offset1:212
	s_waitcnt lgkmcnt(1)
	v_mfma_f32_16x16x32_bf16 v[102:105], v[244:247], v[72:75], v[102:105]
	ds_read2_b64 v[244:247], v150 offset0:240 offset1:244
	s_waitcnt lgkmcnt(1)
	v_mfma_f32_16x16x32_bf16 v[106:109], v[240:243], v[72:75], v[106:109]
	ds_read2_b64 v[240:243], v144 offset0:24 offset1:28
	s_waitcnt lgkmcnt(1)
	v_mfma_f32_16x16x32_bf16 v[140:143], v[244:247], v[72:75], v[84:87]
	ds_read2_b64 v[244:247], v110 offset0:56 offset1:60
	s_waitcnt lgkmcnt(1)
	v_mfma_f32_16x16x32_bf16 v[92:95], v[240:243], v[64:67], v[68:71]
	ds_read2_b64 v[240:243], v111 offset0:88 offset1:92
	s_waitcnt lgkmcnt(1)
	v_mfma_f32_16x16x32_bf16 v[88:91], v[244:247], v[64:67], v[76:79]
	ds_read2_b64 v[244:247], v146 offset0:120 offset1:124
	s_waitcnt lgkmcnt(1)
	v_mfma_f32_16x16x32_bf16 v[84:87], v[240:243], v[64:67], v[80:83]
	ds_read2_b64 v[240:243], v147 offset0:152 offset1:156
	s_waitcnt lgkmcnt(1)
	v_mfma_f32_16x16x32_bf16 v[80:83], v[244:247], v[64:67], v[136:139]
	s_waitcnt lgkmcnt(0)
	v_mfma_f32_16x16x32_bf16 v[76:79], v[240:243], v[64:67], v[98:101]
	ds_read2_b64 v[68:71], v148 offset0:184 offset1:188
	s_nop 1
	ds_read2_b64 v[98:101], v150 offset0:248 offset1:252
	s_waitcnt lgkmcnt(1)
	v_mfma_f32_16x16x32_bf16 v[72:75], v[68:71], v[64:67], v[102:105]
	ds_read2_b64 v[68:71], v149 offset0:216 offset1:220
	s_waitcnt lgkmcnt(0)
	v_mfma_f32_16x16x32_bf16 v[68:71], v[68:71], v[64:67], v[106:109]
	v_mfma_f32_16x16x32_bf16 v[64:67], v[98:101], v[64:67], v[140:143]
	s_and_b64 vcc, exec, s[6:7]
	s_waitcnt vmcnt(7)
	ds_write_b128 v162, v[44:47]
	s_waitcnt vmcnt(6)
	ds_write_b128 v162, v[40:43] offset:8704
	s_waitcnt vmcnt(5)
	ds_write_b128 v162, v[36:39] offset:17408
	s_waitcnt vmcnt(4)
	ds_write_b128 v162, v[32:35] offset:26112
	s_waitcnt vmcnt(3)
	ds_write_b128 v162, v[28:31] offset:34816
	s_waitcnt vmcnt(2)
	ds_write_b128 v162, v[24:27] offset:43520
	s_waitcnt vmcnt(1)
	ds_write_b128 v162, v[16:19] offset:52224
	s_waitcnt vmcnt(0)
	ds_write_b128 v162, v[20:23] offset:60928
	s_waitcnt lgkmcnt(0)
	s_barrier
	s_cbranch_vccnz .LBB0_231
	global_load_dwordx4 v[4:7], v[114:115], off offset:512
	global_load_dwordx4 v[0:3], v[114:115], off offset:576
	global_load_dwordx4 v[8:11], v[114:115], off offset:640
	global_load_dwordx4 v[12:15], v[114:115], off offset:704
